# speedup vs baseline: 1.0210x; 1.0074x over previous
; __device__ __forceinline__ unsigned cvt_pk_bf16(float lo, float hi) { unsigned r; asm volatile("v_cvt_pk_bf16_f32 %0, %1, %2" : "=v"(r) : "v"(lo), "v"(hi)); return r; }
;     __device__ __forceinline__ void operator()(const f32x4 (&acc)[2][2][4][2], const Unit& u, int wr, int wc, int fr, int fq) const {
;         const int row0 = u.pm * BM + wr * 64 + fr, col0 = u.pn * HALF + wc * 32 + 8 * fq;
; #pragma unroll
;         for (int ai = 0; ai < 2; ++ai)
; #pragma unroll
;             for (int m = 0; m < 4; ++m) { const int row = row0 + ai * HALF + m * 16; bf16_t* p = U + (size_t)row * ldu + col0;
;                 const float rs = rsqrtf(SS[row] * (1.f / 2048.f) + 1e-6f);
;                 float r[8];
; #pragma unroll
;                 for (int n = 0; n < 2; ++n)
; #pragma unroll
;                     for (int j = 0; j < 4; ++j) { const float a = acc[ai][0][m][n][j] * rs, b = acc[ai][1][m][n][j] * rs; r[n * 4 + j] = a * __builtin_amdgcn_rcpf(1.f + __expf(-a)) * b; }
;                 u32x4 w; w.x = cvt_pk_bf16(r[0], r[1]); w.y = cvt_pk_bf16(r[2], r[3]); w.z = cvt_pk_bf16(r[4], r[5]); w.w = cvt_pk_bf16(r[6], r[7]);
;                 *(u32x4*)p = w; }
.LBB0_40:
	v_lshl_add_u32 v140, s0, 8, v145
	v_ashrrev_i32_e32 v141, 31, v140
	v_lshl_add_u64 v[150:151], v[140:141], 2, s[10:11]
	global_load_dword v141, v[150:151], off
	global_load_dword v200, v[150:151], off offset:64
	global_load_dword v201, v[150:151], off offset:128
	global_load_dword v202, v[150:151], off offset:192
	global_load_dword v203, v[150:151], off offset:512
	global_load_dword v204, v[150:151], off offset:576
	global_load_dword v205, v[150:151], off offset:640
	global_load_dword v206, v[150:151], off offset:704
	v_mov_b32_e32 v159, v124
	v_mov_b32_e32 v124, v121
	v_mov_b32_e32 v158, v120
	v_lshl_or_b32 v152, s1, 7, v156
	v_ashrrev_i32_e32 v153, 31, v152
	v_mov_b64_e32 v[142:143], s[8:9]
	v_mad_i64_i32 v[154:155], s[0:1], v140, s61, v[142:143]
	v_readlane_b32 s52, v254, 34
	v_readlane_b32 s54, v254, 36
	v_readlane_b32 s55, v254, 37
	v_readlane_b32 s53, v254, 35
	s_waitcnt vmcnt(7)
	v_fmamk_f32 v141, v141, 0x3a000000, v173
	v_cmp_gt_f32_e32 vcc, s76, v141
	v_mul_f32_e32 v146, 0x4b800000, v141
	s_nop 0
	v_cndmask_b32_e32 v141, v141, v146, vcc
	v_rsq_f32_e32 v141, v141
	s_nop 0
	v_mul_f32_e32 v146, 0x45800000, v141
	v_cndmask_b32_e32 v146, v141, v146, vcc
	v_pk_mul_f32 v[124:125], v[124:125], v[146:147] op_sel_hi:[1,0]
	v_pk_mul_f32 v[158:159], v[158:159], v[146:147] op_sel_hi:[1,0]
	v_mul_f32_e32 v121, 0xbfb8aa3b, v125
	v_exp_f32_e32 v121, v121
	v_mul_f32_e32 v120, 0xbfb8aa3b, v159
	v_exp_f32_e32 v120, v120
	v_add_f32_e32 v121, 1.0, v121
	v_rcp_f32_e32 v121, v121
	v_add_f32_e32 v120, 1.0, v120
	v_rcp_f32_e32 v120, v120
	v_mul_f32_e32 v121, v125, v121
	v_mul_f32_e32 v121, v124, v121
	v_mov_b32_e32 v124, v122
	v_mov_b32_e32 v125, v126
	v_pk_mul_f32 v[124:125], v[124:125], v[146:147] op_sel_hi:[1,0]
	v_mov_b32_e32 v126, v123
	v_mul_f32_e32 v122, 0xbfb8aa3b, v125
	v_exp_f32_e32 v122, v122
	v_mul_f32_e32 v120, v159, v120
	v_mul_f32_e32 v120, v158, v120
	v_add_f32_e32 v122, 1.0, v122
	v_rcp_f32_e32 v122, v122
	s_nop 0
	v_mul_f32_e32 v122, v125, v122
	v_mul_f32_e32 v124, v124, v122
	v_pk_mul_f32 v[122:123], v[126:127], v[146:147] op_sel_hi:[1,0]
	s_nop 0
	v_mul_f32_e32 v125, 0xbfb8aa3b, v123
	v_exp_f32_e32 v125, v125
	s_nop 0
	v_add_f32_e32 v125, 1.0, v125
	v_rcp_f32_e32 v125, v125
	s_nop 0
	v_mul_f32_e32 v123, v123, v125
	v_mul_f32_e32 v125, v122, v123
	v_mov_b32_e32 v122, v112
	v_mov_b32_e32 v123, v116
	v_pk_mul_f32 v[122:123], v[122:123], v[146:147] op_sel_hi:[1,0]
	v_mov_b32_e32 v116, v113
	v_mul_f32_e32 v112, 0xbfb8aa3b, v123
	v_exp_f32_e32 v112, v112
	s_nop 0
	v_add_f32_e32 v112, 1.0, v112
	v_rcp_f32_e32 v112, v112
	s_nop 0
	v_mul_f32_e32 v112, v123, v112
	v_mul_f32_e32 v122, v122, v112
	v_pk_mul_f32 v[112:113], v[116:117], v[146:147] op_sel_hi:[1,0]
	s_nop 0
	v_mul_f32_e32 v116, 0xbfb8aa3b, v113
	v_exp_f32_e32 v116, v116
	s_nop 0
	v_add_f32_e32 v116, 1.0, v116
	v_rcp_f32_e32 v116, v116
	s_nop 0
	v_mul_f32_e32 v113, v113, v116
	v_mul_f32_e32 v116, v112, v113
	v_mov_b32_e32 v112, v114
	v_mov_b32_e32 v113, v118
	v_pk_mul_f32 v[112:113], v[112:113], v[146:147] op_sel_hi:[1,0]
	v_mov_b32_e32 v118, v115
	v_mul_f32_e32 v114, 0xbfb8aa3b, v113
	v_exp_f32_e32 v114, v114
	s_nop 0
	v_add_f32_e32 v114, 1.0, v114
	v_rcp_f32_e32 v114, v114
	s_nop 0
	v_mul_f32_e32 v113, v113, v114
	v_mul_f32_e32 v117, v112, v113
	v_pk_mul_f32 v[112:113], v[118:119], v[146:147] op_sel_hi:[1,0]
	s_nop 0
	v_mul_f32_e32 v114, 0xbfb8aa3b, v113
	v_exp_f32_e32 v114, v114
	s_nop 0
	v_add_f32_e32 v114, 1.0, v114
	v_rcp_f32_e32 v114, v114
	s_nop 0
	v_mul_f32_e32 v113, v113, v114
	v_mul_f32_e32 v123, v112, v113
	v_lshlrev_b64 v[112:113], 1, v[152:153]
	v_lshl_add_u64 v[118:119], v[154:155], 0, v[112:113]
	v_cvt_pk_bf16_f32 v114, v120, v121
	v_cvt_pk_bf16_f32 v115, v124, v125
	v_cvt_pk_bf16_f32 v116, v122, v116
	v_cvt_pk_bf16_f32 v117, v117, v123
	global_store_dwordx4 v[118:119], v[114:117], off
	v_mov_b32_e32 v119, v108
	v_mov_b32_e32 v108, v105
	v_mov_b32_e32 v118, v104
	v_or_b32_e32 v114, 16, v140
	v_mad_i64_i32 v[114:115], s[0:1], v114, s61, v[142:143]
	s_waitcnt vmcnt(7)
	v_mov_b32_e32 v116, v200
	v_fmamk_f32 v116, v116, 0x3a000000, v173
	v_cmp_gt_f32_e32 vcc, s76, v116
	v_mul_f32_e32 v117, 0x4b800000, v116
	s_nop 0
	v_cndmask_b32_e32 v116, v116, v117, vcc
	v_rsq_f32_e32 v116, v116
	s_nop 0
	v_mul_f32_e32 v117, 0x45800000, v116
	v_cndmask_b32_e32 v116, v116, v117, vcc
	v_pk_mul_f32 v[108:109], v[108:109], v[116:117] op_sel_hi:[1,0]
	v_pk_mul_f32 v[118:119], v[118:119], v[116:117] op_sel_hi:[1,0]
	v_mul_f32_e32 v105, 0xbfb8aa3b, v109
	v_exp_f32_e32 v105, v105
	v_mul_f32_e32 v104, 0xbfb8aa3b, v119
	v_exp_f32_e32 v104, v104
	v_add_f32_e32 v105, 1.0, v105
	v_rcp_f32_e32 v105, v105
	v_add_f32_e32 v104, 1.0, v104
	v_rcp_f32_e32 v104, v104
	v_mul_f32_e32 v105, v109, v105
	v_mul_f32_e32 v105, v108, v105
	v_mov_b32_e32 v108, v106
	v_mov_b32_e32 v109, v110
	v_pk_mul_f32 v[108:109], v[108:109], v[116:117] op_sel_hi:[1,0]
	v_mov_b32_e32 v110, v107
	v_mul_f32_e32 v106, 0xbfb8aa3b, v109
	v_exp_f32_e32 v106, v106
	v_mul_f32_e32 v104, v119, v104
	v_mul_f32_e32 v104, v118, v104
	v_add_f32_e32 v106, 1.0, v106
	v_rcp_f32_e32 v106, v106
	s_nop 0
	v_mul_f32_e32 v106, v109, v106
	v_mul_f32_e32 v108, v108, v106
	v_pk_mul_f32 v[106:107], v[110:111], v[116:117] op_sel_hi:[1,0]
	s_nop 0
	v_mul_f32_e32 v109, 0xbfb8aa3b, v107
	v_exp_f32_e32 v109, v109
	s_nop 0
	v_add_f32_e32 v109, 1.0, v109
	v_rcp_f32_e32 v109, v109
	s_nop 0
	v_mul_f32_e32 v107, v107, v109
	v_mul_f32_e32 v109, v106, v107
	v_mov_b32_e32 v106, v96
	v_mov_b32_e32 v107, v100
	v_pk_mul_f32 v[106:107], v[106:107], v[116:117] op_sel_hi:[1,0]
	v_mov_b32_e32 v100, v97
	v_mul_f32_e32 v96, 0xbfb8aa3b, v107
	v_exp_f32_e32 v96, v96
	s_nop 0
	v_add_f32_e32 v96, 1.0, v96
	v_rcp_f32_e32 v96, v96
	s_nop 0
	v_mul_f32_e32 v96, v107, v96
	v_mul_f32_e32 v106, v106, v96
	v_pk_mul_f32 v[96:97], v[100:101], v[116:117] op_sel_hi:[1,0]
	s_nop 0
	v_mul_f32_e32 v100, 0xbfb8aa3b, v97
	v_exp_f32_e32 v100, v100
	s_nop 0
	v_add_f32_e32 v100, 1.0, v100
	v_rcp_f32_e32 v100, v100
	s_nop 0
	v_mul_f32_e32 v97, v97, v100
	v_mul_f32_e32 v107, v96, v97
	v_mov_b32_e32 v96, v98
	v_mov_b32_e32 v97, v102
	v_pk_mul_f32 v[96:97], v[96:97], v[116:117] op_sel_hi:[1,0]
	v_mov_b32_e32 v102, v99
	v_mul_f32_e32 v98, 0xbfb8aa3b, v97
	v_exp_f32_e32 v98, v98
	v_lshl_add_u64 v[100:101], v[114:115], 0, v[112:113]
	v_add_f32_e32 v98, 1.0, v98
	v_rcp_f32_e32 v98, v98
	s_nop 0
	v_mul_f32_e32 v97, v97, v98
	v_mul_f32_e32 v110, v96, v97
	v_pk_mul_f32 v[96:97], v[102:103], v[116:117] op_sel_hi:[1,0]
	s_nop 0
	v_mul_f32_e32 v98, 0xbfb8aa3b, v97
	v_exp_f32_e32 v98, v98
	s_nop 0
	v_add_f32_e32 v98, 1.0, v98
	v_rcp_f32_e32 v98, v98
	s_nop 0
	v_mul_f32_e32 v97, v97, v98
	v_mul_f32_e32 v99, v96, v97
	v_cvt_pk_bf16_f32 v96, v104, v105
	v_cvt_pk_bf16_f32 v97, v108, v109
	v_cvt_pk_bf16_f32 v98, v106, v107
	v_cvt_pk_bf16_f32 v99, v110, v99
	global_store_dwordx4 v[100:101], v[96:99], off
	v_mov_b32_e32 v101, v92
	v_mov_b32_e32 v92, v89
	v_mov_b32_e32 v100, v88
	v_or_b32_e32 v96, 32, v140
	v_mad_i64_i32 v[96:97], s[0:1], v96, s61, v[142:143]
	s_waitcnt vmcnt(7)
; __device__ __forceinline__ unsigned cvt_pk_bf16(float lo, float hi) { unsigned r; asm volatile("v_cvt_pk_bf16_f32 %0, %1, %2" : "=v"(r) : "v"(lo), "v"(hi)); return r; }
;     __device__ __forceinline__ void operator()(const f32x4 (&acc)[2][2][4][2], const Unit& u, int wr, int wc, int fr, int fq) const {
;         const int row0 = u.pm * BM + wr * 64 + fr, col0 = u.pn * HALF + wc * 32 + 8 * fq;
; #pragma unroll
;         for (int ai = 0; ai < 2; ++ai)
; #pragma unroll
;             for (int m = 0; m < 4; ++m) { const int row = row0 + ai * HALF + m * 16; bf16_t* p = U + (size_t)row * ldu + col0;
;                 const float rs = rsqrtf(SS[row] * (1.f / 2048.f) + 1e-6f);
;                 float r[8];
; #pragma unroll
;                 for (int n = 0; n < 2; ++n)
; #pragma unroll
;                     for (int j = 0; j < 4; ++j) { const float a = acc[ai][0][m][n][j] * rs, b = acc[ai][1][m][n][j] * rs; r[n * 4 + j] = a * __builtin_amdgcn_rcpf(1.f + __expf(-a)) * b; }
;                 u32x4 w; w.x = cvt_pk_bf16(r[0], r[1]); w.y = cvt_pk_bf16(r[2], r[3]); w.z = cvt_pk_bf16(r[4], r[5]); w.w = cvt_pk_bf16(r[6], r[7]);
;                 *(u32x4*)p = w; }
	v_mov_b32_e32 v98, v201
	v_fmamk_f32 v98, v98, 0x3a000000, v173
	v_cmp_gt_f32_e32 vcc, s76, v98
	v_mul_f32_e32 v99, 0x4b800000, v98
	s_nop 0
	v_cndmask_b32_e32 v98, v98, v99, vcc
	v_rsq_f32_e32 v98, v98
	s_nop 0
	v_mul_f32_e32 v99, 0x45800000, v98
	v_cndmask_b32_e32 v98, v98, v99, vcc
	v_pk_mul_f32 v[92:93], v[92:93], v[98:99] op_sel_hi:[1,0]
	v_pk_mul_f32 v[100:101], v[100:101], v[98:99] op_sel_hi:[1,0]
	v_mul_f32_e32 v89, 0xbfb8aa3b, v93
	v_exp_f32_e32 v89, v89
	v_mul_f32_e32 v88, 0xbfb8aa3b, v101
	v_exp_f32_e32 v88, v88
	v_add_f32_e32 v89, 1.0, v89
	v_rcp_f32_e32 v89, v89
	v_add_f32_e32 v88, 1.0, v88
	v_rcp_f32_e32 v88, v88
	v_mul_f32_e32 v89, v93, v89
	v_mul_f32_e32 v89, v92, v89
	v_mov_b32_e32 v92, v90
	v_mov_b32_e32 v93, v94
	v_pk_mul_f32 v[92:93], v[92:93], v[98:99] op_sel_hi:[1,0]
	v_mov_b32_e32 v94, v91
	v_mul_f32_e32 v90, 0xbfb8aa3b, v93
	v_exp_f32_e32 v90, v90
	v_mul_f32_e32 v88, v101, v88
	v_mul_f32_e32 v88, v100, v88
	v_add_f32_e32 v90, 1.0, v90
	v_rcp_f32_e32 v90, v90
	s_nop 0
	v_mul_f32_e32 v90, v93, v90
	v_mul_f32_e32 v92, v92, v90
	v_pk_mul_f32 v[90:91], v[94:95], v[98:99] op_sel_hi:[1,0]
	s_nop 0
	v_mul_f32_e32 v93, 0xbfb8aa3b, v91
	v_exp_f32_e32 v93, v93
	s_nop 0
	v_add_f32_e32 v93, 1.0, v93
	v_rcp_f32_e32 v93, v93
	s_nop 0
	v_mul_f32_e32 v91, v91, v93
	v_mul_f32_e32 v93, v90, v91
	v_mov_b32_e32 v90, v80
	v_mov_b32_e32 v91, v84
	v_pk_mul_f32 v[90:91], v[90:91], v[98:99] op_sel_hi:[1,0]
	v_mov_b32_e32 v84, v81
	v_mul_f32_e32 v80, 0xbfb8aa3b, v91
	v_exp_f32_e32 v80, v80
	s_nop 0
	v_add_f32_e32 v80, 1.0, v80
	v_rcp_f32_e32 v80, v80
	s_nop 0
	v_mul_f32_e32 v80, v91, v80
	v_mul_f32_e32 v90, v90, v80
	v_pk_mul_f32 v[80:81], v[84:85], v[98:99] op_sel_hi:[1,0]
	s_nop 0
	v_mul_f32_e32 v84, 0xbfb8aa3b, v81
	v_exp_f32_e32 v84, v84
	s_nop 0
	v_add_f32_e32 v84, 1.0, v84
	v_rcp_f32_e32 v84, v84
	s_nop 0
	v_mul_f32_e32 v81, v81, v84
	v_mul_f32_e32 v91, v80, v81
	v_mov_b32_e32 v80, v82
	v_mov_b32_e32 v81, v86
	v_pk_mul_f32 v[80:81], v[80:81], v[98:99] op_sel_hi:[1,0]
	v_mov_b32_e32 v86, v83
	v_mul_f32_e32 v82, 0xbfb8aa3b, v81
	v_exp_f32_e32 v82, v82
	v_lshl_add_u64 v[84:85], v[96:97], 0, v[112:113]
	v_add_f32_e32 v82, 1.0, v82
	v_rcp_f32_e32 v82, v82
	s_nop 0
	v_mul_f32_e32 v81, v81, v82
	v_mul_f32_e32 v94, v80, v81
	v_pk_mul_f32 v[80:81], v[86:87], v[98:99] op_sel_hi:[1,0]
	s_nop 0
	v_mul_f32_e32 v82, 0xbfb8aa3b, v81
	v_exp_f32_e32 v82, v82
	s_nop 0
	v_add_f32_e32 v82, 1.0, v82
	v_rcp_f32_e32 v82, v82
	s_nop 0
	v_mul_f32_e32 v81, v81, v82
	v_mul_f32_e32 v83, v80, v81
	v_cvt_pk_bf16_f32 v80, v88, v89
	v_cvt_pk_bf16_f32 v81, v92, v93
	v_cvt_pk_bf16_f32 v82, v90, v91
	v_cvt_pk_bf16_f32 v83, v94, v83
	global_store_dwordx4 v[84:85], v[80:83], off
	v_mov_b32_e32 v85, v76
	v_mov_b32_e32 v76, v73
	v_mov_b32_e32 v84, v72
	v_or_b32_e32 v80, 48, v140
	v_mad_i64_i32 v[80:81], s[0:1], v80, s61, v[142:143]
	s_waitcnt vmcnt(7)
	v_mov_b32_e32 v82, v202
	v_fmamk_f32 v82, v82, 0x3a000000, v173
	v_cmp_gt_f32_e32 vcc, s76, v82
	v_mul_f32_e32 v83, 0x4b800000, v82
	s_nop 0
	v_cndmask_b32_e32 v82, v82, v83, vcc
	v_rsq_f32_e32 v82, v82
	s_nop 0
	v_mul_f32_e32 v83, 0x45800000, v82
	v_cndmask_b32_e32 v82, v82, v83, vcc
	v_pk_mul_f32 v[76:77], v[76:77], v[82:83] op_sel_hi:[1,0]
	v_pk_mul_f32 v[84:85], v[84:85], v[82:83] op_sel_hi:[1,0]
	v_mul_f32_e32 v73, 0xbfb8aa3b, v77
	v_exp_f32_e32 v73, v73
	v_mul_f32_e32 v72, 0xbfb8aa3b, v85
	v_exp_f32_e32 v72, v72
	v_add_f32_e32 v73, 1.0, v73
	v_rcp_f32_e32 v73, v73
	v_add_f32_e32 v72, 1.0, v72
	v_rcp_f32_e32 v72, v72
	v_mul_f32_e32 v73, v77, v73
	v_mul_f32_e32 v73, v76, v73
	v_mov_b32_e32 v76, v74
	v_mov_b32_e32 v77, v78
	v_pk_mul_f32 v[76:77], v[76:77], v[82:83] op_sel_hi:[1,0]
	v_mov_b32_e32 v78, v75
	v_mul_f32_e32 v74, 0xbfb8aa3b, v77
	v_exp_f32_e32 v74, v74
	v_mul_f32_e32 v72, v85, v72
	v_mul_f32_e32 v72, v84, v72
	v_add_f32_e32 v74, 1.0, v74
	v_rcp_f32_e32 v74, v74
	s_nop 0
	v_mul_f32_e32 v74, v77, v74
	v_mul_f32_e32 v76, v76, v74
	v_pk_mul_f32 v[74:75], v[78:79], v[82:83] op_sel_hi:[1,0]
	s_nop 0
	v_mul_f32_e32 v77, 0xbfb8aa3b, v75
	v_exp_f32_e32 v77, v77
	s_nop 0
	v_add_f32_e32 v77, 1.0, v77
	v_rcp_f32_e32 v77, v77
	s_nop 0
	v_mul_f32_e32 v75, v75, v77
	v_mul_f32_e32 v77, v74, v75
	v_mov_b32_e32 v74, v64
	v_mov_b32_e32 v75, v68
	v_pk_mul_f32 v[74:75], v[74:75], v[82:83] op_sel_hi:[1,0]
	v_mov_b32_e32 v68, v65
	v_mul_f32_e32 v64, 0xbfb8aa3b, v75
	v_exp_f32_e32 v64, v64
	s_nop 0
	v_add_f32_e32 v64, 1.0, v64
	v_rcp_f32_e32 v64, v64
	s_nop 0
	v_mul_f32_e32 v64, v75, v64
	v_mul_f32_e32 v74, v74, v64
	v_pk_mul_f32 v[64:65], v[68:69], v[82:83] op_sel_hi:[1,0]
	s_nop 0
	v_mul_f32_e32 v68, 0xbfb8aa3b, v65
	v_exp_f32_e32 v68, v68
	s_nop 0
	v_add_f32_e32 v68, 1.0, v68
	v_rcp_f32_e32 v68, v68
	s_nop 0
	v_mul_f32_e32 v65, v65, v68
	v_mul_f32_e32 v75, v64, v65
	v_mov_b32_e32 v64, v66
	v_mov_b32_e32 v65, v70
	v_pk_mul_f32 v[64:65], v[64:65], v[82:83] op_sel_hi:[1,0]
	v_mov_b32_e32 v70, v67
	v_mul_f32_e32 v66, 0xbfb8aa3b, v65
	v_exp_f32_e32 v66, v66
	v_lshl_add_u64 v[68:69], v[80:81], 0, v[112:113]
	v_add_f32_e32 v66, 1.0, v66
	v_rcp_f32_e32 v66, v66
	s_nop 0
	v_mul_f32_e32 v65, v65, v66
	v_mul_f32_e32 v78, v64, v65
	v_pk_mul_f32 v[64:65], v[70:71], v[82:83] op_sel_hi:[1,0]
	s_nop 0
	v_mul_f32_e32 v66, 0xbfb8aa3b, v65
	v_exp_f32_e32 v66, v66
	s_nop 0
	v_add_f32_e32 v66, 1.0, v66
	v_rcp_f32_e32 v66, v66
	s_nop 0
	v_mul_f32_e32 v65, v65, v66
	v_mul_f32_e32 v67, v64, v65
	v_cvt_pk_bf16_f32 v64, v72, v73
	v_cvt_pk_bf16_f32 v65, v76, v77
	v_cvt_pk_bf16_f32 v66, v74, v75
	v_cvt_pk_bf16_f32 v67, v78, v67
	global_store_dwordx4 v[68:69], v[64:67], off
	v_mov_b32_e32 v69, v60
	v_mov_b32_e32 v60, v57
	v_mov_b32_e32 v68, v56
	v_add_u32_e32 v64, 0x80, v140
	v_mad_i64_i32 v[64:65], s[0:1], v64, s61, v[142:143]
	s_waitcnt vmcnt(7)
; __device__ __forceinline__ unsigned cvt_pk_bf16(float lo, float hi) { unsigned r; asm volatile("v_cvt_pk_bf16_f32 %0, %1, %2" : "=v"(r) : "v"(lo), "v"(hi)); return r; }
;     __device__ __forceinline__ void operator()(const f32x4 (&acc)[2][2][4][2], const Unit& u, int wr, int wc, int fr, int fq) const {
;         const int row0 = u.pm * BM + wr * 64 + fr, col0 = u.pn * HALF + wc * 32 + 8 * fq;
; #pragma unroll
;         for (int ai = 0; ai < 2; ++ai)
; #pragma unroll
;             for (int m = 0; m < 4; ++m) { const int row = row0 + ai * HALF + m * 16; bf16_t* p = U + (size_t)row * ldu + col0;
;                 const float rs = rsqrtf(SS[row] * (1.f / 2048.f) + 1e-6f);
;                 float r[8];
; #pragma unroll
;                 for (int n = 0; n < 2; ++n)
; #pragma unroll
;                     for (int j = 0; j < 4; ++j) { const float a = acc[ai][0][m][n][j] * rs, b = acc[ai][1][m][n][j] * rs; r[n * 4 + j] = a * __builtin_amdgcn_rcpf(1.f + __expf(-a)) * b; }
;                 u32x4 w; w.x = cvt_pk_bf16(r[0], r[1]); w.y = cvt_pk_bf16(r[2], r[3]); w.z = cvt_pk_bf16(r[4], r[5]); w.w = cvt_pk_bf16(r[6], r[7]);
;                 *(u32x4*)p = w; }
	v_mov_b32_e32 v66, v203
	v_fmamk_f32 v66, v66, 0x3a000000, v173
	v_cmp_gt_f32_e32 vcc, s76, v66
	v_mul_f32_e32 v67, 0x4b800000, v66
	s_nop 0
	v_cndmask_b32_e32 v66, v66, v67, vcc
	v_rsq_f32_e32 v66, v66
	s_nop 0
	v_mul_f32_e32 v67, 0x45800000, v66
	v_cndmask_b32_e32 v66, v66, v67, vcc
	v_pk_mul_f32 v[60:61], v[60:61], v[66:67] op_sel_hi:[1,0]
	v_pk_mul_f32 v[68:69], v[68:69], v[66:67] op_sel_hi:[1,0]
	v_mul_f32_e32 v57, 0xbfb8aa3b, v61
	v_exp_f32_e32 v57, v57
	v_mul_f32_e32 v56, 0xbfb8aa3b, v69
	v_exp_f32_e32 v56, v56
	v_add_f32_e32 v57, 1.0, v57
	v_rcp_f32_e32 v57, v57
	v_add_f32_e32 v56, 1.0, v56
	v_rcp_f32_e32 v56, v56
	v_mul_f32_e32 v57, v61, v57
	v_mul_f32_e32 v57, v60, v57
	v_mov_b32_e32 v60, v58
	v_mov_b32_e32 v61, v62
	v_pk_mul_f32 v[60:61], v[60:61], v[66:67] op_sel_hi:[1,0]
	v_mov_b32_e32 v62, v59
	v_mul_f32_e32 v58, 0xbfb8aa3b, v61
	v_exp_f32_e32 v58, v58
	v_mul_f32_e32 v56, v69, v56
	v_mul_f32_e32 v56, v68, v56
	v_add_f32_e32 v58, 1.0, v58
	v_rcp_f32_e32 v58, v58
	s_nop 0
	v_mul_f32_e32 v58, v61, v58
	v_mul_f32_e32 v60, v60, v58
	v_pk_mul_f32 v[58:59], v[62:63], v[66:67] op_sel_hi:[1,0]
	s_nop 0
	v_mul_f32_e32 v61, 0xbfb8aa3b, v59
	v_exp_f32_e32 v61, v61
	s_nop 0
	v_add_f32_e32 v61, 1.0, v61
	v_rcp_f32_e32 v61, v61
	s_nop 0
	v_mul_f32_e32 v59, v59, v61
	v_mul_f32_e32 v61, v58, v59
	v_mov_b32_e32 v58, v48
	v_mov_b32_e32 v59, v52
	v_pk_mul_f32 v[58:59], v[58:59], v[66:67] op_sel_hi:[1,0]
	v_mov_b32_e32 v52, v49
	v_mul_f32_e32 v48, 0xbfb8aa3b, v59
	v_exp_f32_e32 v48, v48
	s_nop 0
	v_add_f32_e32 v48, 1.0, v48
	v_rcp_f32_e32 v48, v48
	s_nop 0
	v_mul_f32_e32 v48, v59, v48
	v_mul_f32_e32 v58, v58, v48
	v_pk_mul_f32 v[48:49], v[52:53], v[66:67] op_sel_hi:[1,0]
	s_nop 0
	v_mul_f32_e32 v52, 0xbfb8aa3b, v49
	v_exp_f32_e32 v52, v52
	s_nop 0
	v_add_f32_e32 v52, 1.0, v52
	v_rcp_f32_e32 v52, v52
	s_nop 0
	v_mul_f32_e32 v49, v49, v52
	v_mul_f32_e32 v59, v48, v49
	v_mov_b32_e32 v48, v50
	v_mov_b32_e32 v49, v54
	v_pk_mul_f32 v[48:49], v[48:49], v[66:67] op_sel_hi:[1,0]
	v_mov_b32_e32 v54, v51
	v_mul_f32_e32 v50, 0xbfb8aa3b, v49
	v_exp_f32_e32 v50, v50
	v_lshl_add_u64 v[52:53], v[64:65], 0, v[112:113]
	v_add_f32_e32 v50, 1.0, v50
	v_rcp_f32_e32 v50, v50
	s_nop 0
	v_mul_f32_e32 v49, v49, v50
	v_mul_f32_e32 v62, v48, v49
	v_pk_mul_f32 v[48:49], v[54:55], v[66:67] op_sel_hi:[1,0]
	s_nop 0
	v_mul_f32_e32 v50, 0xbfb8aa3b, v49
	v_exp_f32_e32 v50, v50
	s_nop 0
	v_add_f32_e32 v50, 1.0, v50
	v_rcp_f32_e32 v50, v50
	s_nop 0
	v_mul_f32_e32 v49, v49, v50
	v_mul_f32_e32 v51, v48, v49
	v_cvt_pk_bf16_f32 v48, v56, v57
	v_cvt_pk_bf16_f32 v49, v60, v61
	v_cvt_pk_bf16_f32 v50, v58, v59
	v_cvt_pk_bf16_f32 v51, v62, v51
	global_store_dwordx4 v[52:53], v[48:51], off
	v_mov_b32_e32 v53, v44
	v_mov_b32_e32 v44, v41
	v_mov_b32_e32 v52, v40
	v_add_u32_e32 v48, 0x90, v140
	v_mad_i64_i32 v[48:49], s[0:1], v48, s61, v[142:143]
	s_waitcnt vmcnt(7)
	v_mov_b32_e32 v50, v204
	v_fmamk_f32 v50, v50, 0x3a000000, v173
	v_cmp_gt_f32_e32 vcc, s76, v50
	v_mul_f32_e32 v51, 0x4b800000, v50
	s_nop 0
	v_cndmask_b32_e32 v50, v50, v51, vcc
	v_rsq_f32_e32 v50, v50
	s_nop 0
	v_mul_f32_e32 v51, 0x45800000, v50
	v_cndmask_b32_e32 v50, v50, v51, vcc
	v_pk_mul_f32 v[44:45], v[44:45], v[50:51] op_sel_hi:[1,0]
	v_pk_mul_f32 v[52:53], v[52:53], v[50:51] op_sel_hi:[1,0]
	v_mul_f32_e32 v41, 0xbfb8aa3b, v45
	v_exp_f32_e32 v41, v41
	v_mul_f32_e32 v40, 0xbfb8aa3b, v53
	v_exp_f32_e32 v40, v40
	v_add_f32_e32 v41, 1.0, v41
	v_rcp_f32_e32 v41, v41
	v_add_f32_e32 v40, 1.0, v40
	v_rcp_f32_e32 v40, v40
	v_mul_f32_e32 v41, v45, v41
	v_mul_f32_e32 v41, v44, v41
	v_mov_b32_e32 v44, v42
	v_mov_b32_e32 v45, v46
	v_pk_mul_f32 v[44:45], v[44:45], v[50:51] op_sel_hi:[1,0]
	v_mov_b32_e32 v46, v43
	v_mul_f32_e32 v42, 0xbfb8aa3b, v45
	v_exp_f32_e32 v42, v42
	v_mul_f32_e32 v40, v53, v40
	v_mul_f32_e32 v40, v52, v40
	v_add_f32_e32 v42, 1.0, v42
	v_rcp_f32_e32 v42, v42
	s_nop 0
	v_mul_f32_e32 v42, v45, v42
	v_mul_f32_e32 v44, v44, v42
	v_pk_mul_f32 v[42:43], v[46:47], v[50:51] op_sel_hi:[1,0]
	s_nop 0
	v_mul_f32_e32 v45, 0xbfb8aa3b, v43
	v_exp_f32_e32 v45, v45
	s_nop 0
	v_add_f32_e32 v45, 1.0, v45
	v_rcp_f32_e32 v45, v45
	s_nop 0
	v_mul_f32_e32 v43, v43, v45
	v_mul_f32_e32 v45, v42, v43
	v_mov_b32_e32 v42, v32
	v_mov_b32_e32 v43, v36
	v_pk_mul_f32 v[42:43], v[42:43], v[50:51] op_sel_hi:[1,0]
	v_mov_b32_e32 v36, v33
	v_mul_f32_e32 v32, 0xbfb8aa3b, v43
	v_exp_f32_e32 v32, v32
	s_nop 0
	v_add_f32_e32 v32, 1.0, v32
	v_rcp_f32_e32 v32, v32
	s_nop 0
	v_mul_f32_e32 v32, v43, v32
	v_mul_f32_e32 v42, v42, v32
	v_pk_mul_f32 v[32:33], v[36:37], v[50:51] op_sel_hi:[1,0]
	s_nop 0
	v_mul_f32_e32 v36, 0xbfb8aa3b, v33
	v_exp_f32_e32 v36, v36
	s_nop 0
	v_add_f32_e32 v36, 1.0, v36
	v_rcp_f32_e32 v36, v36
	s_nop 0
	v_mul_f32_e32 v33, v33, v36
	v_mul_f32_e32 v43, v32, v33
	v_mov_b32_e32 v32, v34
	v_mov_b32_e32 v33, v38
	v_pk_mul_f32 v[32:33], v[32:33], v[50:51] op_sel_hi:[1,0]
	v_mov_b32_e32 v38, v35
	v_mul_f32_e32 v34, 0xbfb8aa3b, v33
	v_exp_f32_e32 v34, v34
	v_lshl_add_u64 v[36:37], v[48:49], 0, v[112:113]
	v_add_f32_e32 v34, 1.0, v34
	v_rcp_f32_e32 v34, v34
	s_nop 0
	v_mul_f32_e32 v33, v33, v34
	v_mul_f32_e32 v46, v32, v33
	v_pk_mul_f32 v[32:33], v[38:39], v[50:51] op_sel_hi:[1,0]
	s_nop 0
	v_mul_f32_e32 v34, 0xbfb8aa3b, v33
	v_exp_f32_e32 v34, v34
	s_nop 0
	v_add_f32_e32 v34, 1.0, v34
	v_rcp_f32_e32 v34, v34
	s_nop 0
	v_mul_f32_e32 v33, v33, v34
	v_mul_f32_e32 v35, v32, v33
	v_cvt_pk_bf16_f32 v32, v40, v41
	v_cvt_pk_bf16_f32 v33, v44, v45
	v_cvt_pk_bf16_f32 v34, v42, v43
	v_cvt_pk_bf16_f32 v35, v46, v35
	global_store_dwordx4 v[36:37], v[32:35], off
	v_mov_b32_e32 v37, v28
	v_mov_b32_e32 v28, v25
	v_mov_b32_e32 v36, v24
	v_add_u32_e32 v32, 0xa0, v140
	v_mad_i64_i32 v[32:33], s[0:1], v32, s61, v[142:143]
	s_waitcnt vmcnt(7)
; __device__ __forceinline__ unsigned cvt_pk_bf16(float lo, float hi) { unsigned r; asm volatile("v_cvt_pk_bf16_f32 %0, %1, %2" : "=v"(r) : "v"(lo), "v"(hi)); return r; }
; #define PG8_BAR __builtin_amdgcn_s_barrier()
; template <class Epi, class Sched, bool ALIGN_EPI = false, bool SP2 = false>
; __device__ __forceinline__ void gemm_phase(PG8_LAS unsigned char* lds, const Gemm g, const Sched& S, const Epi& E) {
;     ...
;         if constexpr (ALIGN_EPI) { if (wr == 0) PG8_BAR; }
;         if constexpr (!Epi::AFTER_DRAIN) { E(acc, cur, wr, wc, fr, fq); S.done(cur); }
;         if (!has_next) break;
; #pragma unroll
;         for (int a = 0; a < 2; ++a)
; #pragma unroll
;             for (int b = 0; b < 2; ++b)
; #pragma unroll
;                 for (int m = 0; m < 4; ++m)
; #pragma unroll
;                     for (int n = 0; n < 2; ++n) acc[a][b][m][n] = (f32x4){0.f, 0.f, 0.f, 0.f};
;         cur = nxt; cA = nA; cB = nB; ++ui;
;         if constexpr (ALIGN_EPI) { if (wr == 1) PG8_BAR; }
;     __device__ __forceinline__ void operator()(const f32x4 (&acc)[2][2][4][2], const Unit& u, int wr, int wc, int fr, int fq) const {
;         const int row0 = u.pm * BM + wr * 64 + fr, col0 = u.pn * HALF + wc * 32 + 8 * fq;
; #pragma unroll
;         for (int ai = 0; ai < 2; ++ai)
; #pragma unroll
;             for (int m = 0; m < 4; ++m) { const int row = row0 + ai * HALF + m * 16; bf16_t* p = U + (size_t)row * ldu + col0;
;                 const float rs = rsqrtf(SS[row] * (1.f / 2048.f) + 1e-6f);
;                 float r[8];
; #pragma unroll
;                 for (int n = 0; n < 2; ++n)
; #pragma unroll
;                     for (int j = 0; j < 4; ++j) { const float a = acc[ai][0][m][n][j] * rs, b = acc[ai][1][m][n][j] * rs; r[n * 4 + j] = a * __builtin_amdgcn_rcpf(1.f + __expf(-a)) * b; }
;                 u32x4 w; w.x = cvt_pk_bf16(r[0], r[1]); w.y = cvt_pk_bf16(r[2], r[3]); w.z = cvt_pk_bf16(r[4], r[5]); w.w = cvt_pk_bf16(r[6], r[7]);
;                 *(u32x4*)p = w; }
	v_mov_b32_e32 v34, v205
	v_fmamk_f32 v34, v34, 0x3a000000, v173
	v_cmp_gt_f32_e32 vcc, s76, v34
	v_mul_f32_e32 v35, 0x4b800000, v34
	s_nop 0
	v_cndmask_b32_e32 v34, v34, v35, vcc
	v_rsq_f32_e32 v34, v34
	s_nop 0
	v_mul_f32_e32 v35, 0x45800000, v34
	v_cndmask_b32_e32 v34, v34, v35, vcc
	v_pk_mul_f32 v[28:29], v[28:29], v[34:35] op_sel_hi:[1,0]
	v_pk_mul_f32 v[36:37], v[36:37], v[34:35] op_sel_hi:[1,0]
	v_mul_f32_e32 v25, 0xbfb8aa3b, v29
	v_exp_f32_e32 v25, v25
	v_mul_f32_e32 v24, 0xbfb8aa3b, v37
	v_exp_f32_e32 v24, v24
	v_add_f32_e32 v25, 1.0, v25
	v_rcp_f32_e32 v25, v25
	v_add_f32_e32 v24, 1.0, v24
	v_rcp_f32_e32 v24, v24
	v_mul_f32_e32 v25, v29, v25
	v_mul_f32_e32 v25, v28, v25
	v_mov_b32_e32 v28, v26
	v_mov_b32_e32 v29, v30
	v_pk_mul_f32 v[28:29], v[28:29], v[34:35] op_sel_hi:[1,0]
	v_mov_b32_e32 v30, v27
	v_mul_f32_e32 v26, 0xbfb8aa3b, v29
	v_exp_f32_e32 v26, v26
	v_mul_f32_e32 v24, v37, v24
	v_mul_f32_e32 v24, v36, v24
	v_add_f32_e32 v26, 1.0, v26
	v_rcp_f32_e32 v26, v26
	s_nop 0
	v_mul_f32_e32 v26, v29, v26
	v_mul_f32_e32 v28, v28, v26
	v_pk_mul_f32 v[26:27], v[30:31], v[34:35] op_sel_hi:[1,0]
	s_nop 0
	v_mul_f32_e32 v29, 0xbfb8aa3b, v27
	v_exp_f32_e32 v29, v29
	s_nop 0
	v_add_f32_e32 v29, 1.0, v29
	v_rcp_f32_e32 v29, v29
	s_nop 0
	v_mul_f32_e32 v27, v27, v29
	v_mul_f32_e32 v29, v26, v27
	v_mov_b32_e32 v26, v16
	v_mov_b32_e32 v27, v20
	v_pk_mul_f32 v[26:27], v[26:27], v[34:35] op_sel_hi:[1,0]
	v_mov_b32_e32 v20, v17
	v_mul_f32_e32 v16, 0xbfb8aa3b, v27
	v_exp_f32_e32 v16, v16
	s_nop 0
	v_add_f32_e32 v16, 1.0, v16
	v_rcp_f32_e32 v16, v16
	s_nop 0
	v_mul_f32_e32 v16, v27, v16
	v_mul_f32_e32 v26, v26, v16
	v_pk_mul_f32 v[16:17], v[20:21], v[34:35] op_sel_hi:[1,0]
	s_nop 0
	v_mul_f32_e32 v20, 0xbfb8aa3b, v17
	v_exp_f32_e32 v20, v20
	s_nop 0
	v_add_f32_e32 v20, 1.0, v20
	v_rcp_f32_e32 v20, v20
	s_nop 0
	v_mul_f32_e32 v17, v17, v20
	v_mul_f32_e32 v27, v16, v17
	v_mov_b32_e32 v16, v18
	v_mov_b32_e32 v17, v22
	v_pk_mul_f32 v[16:17], v[16:17], v[34:35] op_sel_hi:[1,0]
	v_mov_b32_e32 v22, v19
	v_mul_f32_e32 v18, 0xbfb8aa3b, v17
	v_exp_f32_e32 v18, v18
	v_lshl_add_u64 v[20:21], v[32:33], 0, v[112:113]
	v_add_f32_e32 v18, 1.0, v18
	v_rcp_f32_e32 v18, v18
	s_nop 0
	v_mul_f32_e32 v17, v17, v18
	v_mul_f32_e32 v30, v16, v17
	v_pk_mul_f32 v[16:17], v[22:23], v[34:35] op_sel_hi:[1,0]
	s_nop 0
	v_mul_f32_e32 v18, 0xbfb8aa3b, v17
	v_exp_f32_e32 v18, v18
	s_nop 0
	v_add_f32_e32 v18, 1.0, v18
	v_rcp_f32_e32 v18, v18
	s_nop 0
	v_mul_f32_e32 v17, v17, v18
	v_mul_f32_e32 v19, v16, v17
	v_cvt_pk_bf16_f32 v16, v24, v25
	v_cvt_pk_bf16_f32 v17, v28, v29
	v_cvt_pk_bf16_f32 v18, v26, v27
	v_cvt_pk_bf16_f32 v19, v30, v19
	global_store_dwordx4 v[20:21], v[16:19], off
	v_mov_b32_e32 v20, v8
	v_mov_b32_e32 v21, v12
	v_mov_b32_e32 v12, v9
	v_add_u32_e32 v16, 0xb0, v140
	v_mad_i64_i32 v[16:17], s[0:1], v16, s61, v[142:143]
	s_mov_b64 s[0:1], -1
	s_waitcnt vmcnt(7)
	v_mov_b32_e32 v18, v206
	v_fmamk_f32 v18, v18, 0x3a000000, v173
	v_cmp_gt_f32_e32 vcc, s76, v18
	v_mul_f32_e32 v19, 0x4b800000, v18
	s_nop 0
	v_cndmask_b32_e32 v18, v18, v19, vcc
	v_rsq_f32_e32 v18, v18
	s_nop 0
	v_mul_f32_e32 v19, 0x45800000, v18
	v_cndmask_b32_e32 v18, v18, v19, vcc
	v_pk_mul_f32 v[20:21], v[20:21], v[18:19] op_sel_hi:[1,0]
	s_andn2_b64 vcc, exec, s[38:39]
	v_mul_f32_e32 v8, 0xbfb8aa3b, v21
	v_exp_f32_e32 v8, v8
	s_nop 0
	v_add_f32_e32 v8, 1.0, v8
	v_rcp_f32_e32 v8, v8
	s_nop 0
	v_mul_f32_e32 v8, v21, v8
	v_mul_f32_e32 v19, v20, v8
	v_pk_mul_f32 v[8:9], v[12:13], v[18:19] op_sel_hi:[1,0]
	s_nop 0
	v_mul_f32_e32 v12, 0xbfb8aa3b, v9
	v_exp_f32_e32 v12, v12
	s_nop 0
	v_add_f32_e32 v12, 1.0, v12
	v_rcp_f32_e32 v12, v12
	s_nop 0
	v_mul_f32_e32 v9, v9, v12
	v_mul_f32_e32 v12, v8, v9
	v_mov_b32_e32 v8, v10
	v_mov_b32_e32 v9, v14
	v_pk_mul_f32 v[8:9], v[8:9], v[18:19] op_sel_hi:[1,0]
	v_mov_b32_e32 v14, v11
	v_mul_f32_e32 v10, 0xbfb8aa3b, v9
	v_exp_f32_e32 v10, v10
	s_nop 0
	v_add_f32_e32 v10, 1.0, v10
	v_rcp_f32_e32 v10, v10
	s_nop 0
	v_mul_f32_e32 v9, v9, v10
	v_mul_f32_e32 v10, v8, v9
	v_pk_mul_f32 v[8:9], v[14:15], v[18:19] op_sel_hi:[1,0]
	s_nop 0
	v_mul_f32_e32 v11, 0xbfb8aa3b, v9
	v_exp_f32_e32 v11, v11
	s_nop 0
	v_add_f32_e32 v11, 1.0, v11
	v_rcp_f32_e32 v11, v11
	s_nop 0
	v_mul_f32_e32 v9, v9, v11
	v_mul_f32_e32 v11, v8, v9
	v_mov_b32_e32 v8, v0
	v_mov_b32_e32 v9, v4
	v_pk_mul_f32 v[8:9], v[8:9], v[18:19] op_sel_hi:[1,0]
	v_mov_b32_e32 v4, v1
	v_mul_f32_e32 v0, 0xbfb8aa3b, v9
	v_exp_f32_e32 v0, v0
	s_nop 0
	v_add_f32_e32 v0, 1.0, v0
	v_rcp_f32_e32 v0, v0
	s_nop 0
	v_mul_f32_e32 v0, v9, v0
	v_mul_f32_e32 v8, v8, v0
	v_pk_mul_f32 v[0:1], v[4:5], v[18:19] op_sel_hi:[1,0]
	s_nop 0
	v_mul_f32_e32 v4, 0xbfb8aa3b, v1
	v_exp_f32_e32 v4, v4
	s_nop 0
	v_add_f32_e32 v4, 1.0, v4
	v_rcp_f32_e32 v4, v4
	s_nop 0
	v_mul_f32_e32 v1, v1, v4
	v_mul_f32_e32 v9, v0, v1
	v_mov_b32_e32 v0, v2
	v_mov_b32_e32 v1, v6
	v_pk_mul_f32 v[0:1], v[0:1], v[18:19] op_sel_hi:[1,0]
	v_mov_b32_e32 v6, v3
	v_mul_f32_e32 v2, 0xbfb8aa3b, v1
	v_exp_f32_e32 v2, v2
	v_lshl_add_u64 v[4:5], v[16:17], 0, v[112:113]
	v_add_f32_e32 v2, 1.0, v2
	v_rcp_f32_e32 v2, v2
	s_nop 0
	v_mul_f32_e32 v1, v1, v2
	v_mul_f32_e32 v13, v0, v1
	v_pk_mul_f32 v[0:1], v[6:7], v[18:19] op_sel_hi:[1,0]
	s_nop 0
	v_mul_f32_e32 v2, 0xbfb8aa3b, v1
	v_exp_f32_e32 v2, v2
	s_nop 0
	v_add_f32_e32 v2, 1.0, v2
	v_rcp_f32_e32 v2, v2
	s_nop 0
	v_mul_f32_e32 v1, v1, v2
	v_mul_f32_e32 v3, v0, v1
	v_cvt_pk_bf16_f32 v0, v19, v12
	v_cvt_pk_bf16_f32 v1, v10, v11
	v_cvt_pk_bf16_f32 v2, v8, v9
	v_cvt_pk_bf16_f32 v3, v13, v3
	global_store_dwordx4 v[4:5], v[0:3], off
	s_cbranch_vccnz .LBB0_33
	s_andn2_b64 vcc, exec, s[6:7]
	s_cbranch_vccnz .LBB0_32
	s_barrier
	s_branch .LBB0_32

;     __device__ __forceinline__ void operator()(const f32x4 (&acc)[2][2][4][2], const Unit& u, int wr, int wc, int fr, int fq) const {
;         const int col0 = u.pn * BM + wc * 32 + 4 * fq;
; #pragma unroll
;         for (int ai = 0; ai < 2; ++ai)
; #pragma unroll
;             for (int m = 0; m < 4; ++m) { const int row = u.pm * BM + ai * HALF + wr * 64 + m * 16 + fr; const size_t off = (size_t)row * ldc + col0;
;                 const float rs = rsqrtf(SS[row] * (1.f / 2048.f) + 1e-6f);
; #pragma unroll
;                 for (int bj = 0; bj < 2; ++bj)
; #pragma unroll
;                     for (int n = 0; n < 2; ++n) *(f32x4*)(O + off + bj * HALF + n * 16) = acc[ai][bj][m][n] * rs; }
.LBB0_361:
	v_lshl_add_u32 v136, s0, 8, v138
	v_ashrrev_i32_e32 v137, 31, v136
	v_lshl_add_u64 v[150:151], v[136:137], 2, s[8:9]
	global_load_dword v137, v[150:151], off
	global_load_dword v200, v[150:151], off offset:64
	global_load_dword v201, v[150:151], off offset:128
	global_load_dword v202, v[150:151], off offset:192
	global_load_dword v203, v[150:151], off offset:512
	global_load_dword v204, v[150:151], off offset:576
	global_load_dword v205, v[150:151], off offset:640
	global_load_dword v206, v[150:151], off offset:704
	v_lshl_or_b32 v142, s1, 8, v140
	v_ashrrev_i32_e32 v143, 31, v142
	s_movk_i32 s14, 0x5000
	s_waitcnt vmcnt(7)
	v_fmamk_f32 v137, v137, 0x3a000000, v173
	v_cmp_gt_f32_e32 vcc, s76, v137
	v_mul_f32_e32 v145, 0x4b800000, v137
	s_nop 0
	v_cndmask_b32_e32 v137, v137, v145, vcc
	v_rsq_f32_e32 v137, v137
	s_nop 0
	v_mul_f32_e32 v145, 0x45800000, v137
	v_cndmask_b32_e32 v146, v137, v145, vcc
	v_pk_mul_f32 v[150:151], v[124:125], v[146:147] op_sel_hi:[1,0]
	v_mov_b64_e32 v[124:125], s[6:7]
	v_pk_mul_f32 v[152:153], v[126:127], v[146:147] op_sel_hi:[1,0]
	v_mad_i64_i32 v[154:155], s[0:1], v136, s14, v[124:125]
	v_lshlrev_b64 v[126:127], 2, v[142:143]
	v_lshl_add_u64 v[142:143], v[154:155], 0, v[126:127]
	v_pk_mul_f32 v[114:115], v[114:115], v[146:147] op_sel_hi:[1,0]
	v_pk_mul_f32 v[112:113], v[112:113], v[146:147] op_sel_hi:[1,0]
	global_store_dwordx4 v[142:143], v[112:115], off offset:576
	v_pk_mul_f32 v[122:123], v[122:123], v[146:147] op_sel_hi:[1,0]
	v_pk_mul_f32 v[120:121], v[120:121], v[146:147] op_sel_hi:[1,0]
	v_or_b32_e32 v112, 16, v136
	v_pk_mul_f32 v[118:119], v[118:119], v[146:147] op_sel_hi:[1,0]
	v_pk_mul_f32 v[116:117], v[116:117], v[146:147] op_sel_hi:[1,0]
	v_ashrrev_i32_e32 v113, 31, v112
	global_store_dwordx4 v[142:143], v[150:153], off
	global_store_dwordx4 v[142:143], v[120:123], off offset:64
	global_store_dwordx4 v[142:143], v[116:119], off offset:512
	v_lshl_add_u64 v[114:115], v[112:113], 2, s[8:9]
	s_waitcnt vmcnt(10)
	v_mov_b32_e32 v113, v200
	v_fmamk_f32 v113, v113, 0x3a000000, v173
	v_cmp_gt_f32_e32 vcc, s76, v113
	v_mul_f32_e32 v114, 0x4b800000, v113
	s_nop 0
	v_cndmask_b32_e32 v113, v113, v114, vcc
	v_rsq_f32_e32 v113, v113
	s_nop 0
	v_mul_f32_e32 v114, 0x45800000, v113
	v_cndmask_b32_e32 v114, v113, v114, vcc
	v_mad_i64_i32 v[112:113], s[0:1], v112, s14, v[124:125]
	v_lshl_add_u64 v[112:113], v[112:113], 0, v[126:127]
	v_pk_mul_f32 v[98:99], v[98:99], v[114:115] op_sel_hi:[1,0]
	v_pk_mul_f32 v[96:97], v[96:97], v[114:115] op_sel_hi:[1,0]
	global_store_dwordx4 v[112:113], v[96:99], off offset:576
	v_pk_mul_f32 v[110:111], v[110:111], v[114:115] op_sel_hi:[1,0]
	v_pk_mul_f32 v[108:109], v[108:109], v[114:115] op_sel_hi:[1,0]
	v_or_b32_e32 v96, 32, v136
	v_pk_mul_f32 v[106:107], v[106:107], v[114:115] op_sel_hi:[1,0]
	v_pk_mul_f32 v[104:105], v[104:105], v[114:115] op_sel_hi:[1,0]
	v_pk_mul_f32 v[102:103], v[102:103], v[114:115] op_sel_hi:[1,0]
	v_pk_mul_f32 v[100:101], v[100:101], v[114:115] op_sel_hi:[1,0]
	v_ashrrev_i32_e32 v97, 31, v96
	global_store_dwordx4 v[112:113], v[108:111], off
	global_store_dwordx4 v[112:113], v[104:107], off offset:64
	global_store_dwordx4 v[112:113], v[100:103], off offset:512
	v_lshl_add_u64 v[98:99], v[96:97], 2, s[8:9]
	s_waitcnt vmcnt(13)
	v_mov_b32_e32 v97, v201
	v_fmamk_f32 v97, v97, 0x3a000000, v173
	v_cmp_gt_f32_e32 vcc, s76, v97
	v_mul_f32_e32 v98, 0x4b800000, v97
	s_nop 0
	v_cndmask_b32_e32 v97, v97, v98, vcc
	v_rsq_f32_e32 v97, v97
	s_nop 0
	v_mul_f32_e32 v98, 0x45800000, v97
	v_cndmask_b32_e32 v98, v97, v98, vcc
	v_mad_i64_i32 v[96:97], s[0:1], v96, s14, v[124:125]
	v_lshl_add_u64 v[96:97], v[96:97], 0, v[126:127]
	v_pk_mul_f32 v[82:83], v[82:83], v[98:99] op_sel_hi:[1,0]
	v_pk_mul_f32 v[80:81], v[80:81], v[98:99] op_sel_hi:[1,0]
	global_store_dwordx4 v[96:97], v[80:83], off offset:576
	v_pk_mul_f32 v[94:95], v[94:95], v[98:99] op_sel_hi:[1,0]
	v_pk_mul_f32 v[92:93], v[92:93], v[98:99] op_sel_hi:[1,0]
	v_or_b32_e32 v80, 48, v136
	v_pk_mul_f32 v[90:91], v[90:91], v[98:99] op_sel_hi:[1,0]
	v_pk_mul_f32 v[88:89], v[88:89], v[98:99] op_sel_hi:[1,0]
	v_pk_mul_f32 v[86:87], v[86:87], v[98:99] op_sel_hi:[1,0]
	v_pk_mul_f32 v[84:85], v[84:85], v[98:99] op_sel_hi:[1,0]
	v_ashrrev_i32_e32 v81, 31, v80
	global_store_dwordx4 v[96:97], v[92:95], off
	global_store_dwordx4 v[96:97], v[88:91], off offset:64
	global_store_dwordx4 v[96:97], v[84:87], off offset:512
	v_lshl_add_u64 v[82:83], v[80:81], 2, s[8:9]
	s_waitcnt vmcnt(16)
	v_mov_b32_e32 v81, v202
	v_fmamk_f32 v81, v81, 0x3a000000, v173
	v_cmp_gt_f32_e32 vcc, s76, v81
	v_mul_f32_e32 v82, 0x4b800000, v81
	s_nop 0
	v_cndmask_b32_e32 v81, v81, v82, vcc
	v_rsq_f32_e32 v81, v81
	s_nop 0
	v_mul_f32_e32 v82, 0x45800000, v81
	v_cndmask_b32_e32 v82, v81, v82, vcc
	v_mad_i64_i32 v[80:81], s[0:1], v80, s14, v[124:125]
	v_lshl_add_u64 v[80:81], v[80:81], 0, v[126:127]
	v_pk_mul_f32 v[66:67], v[66:67], v[82:83] op_sel_hi:[1,0]
	v_pk_mul_f32 v[64:65], v[64:65], v[82:83] op_sel_hi:[1,0]
	global_store_dwordx4 v[80:81], v[64:67], off offset:576
	v_pk_mul_f32 v[78:79], v[78:79], v[82:83] op_sel_hi:[1,0]
	v_pk_mul_f32 v[76:77], v[76:77], v[82:83] op_sel_hi:[1,0]
	v_add_u32_e32 v64, 0x80, v136
	v_pk_mul_f32 v[74:75], v[74:75], v[82:83] op_sel_hi:[1,0]
	v_pk_mul_f32 v[72:73], v[72:73], v[82:83] op_sel_hi:[1,0]
	v_pk_mul_f32 v[70:71], v[70:71], v[82:83] op_sel_hi:[1,0]
	v_pk_mul_f32 v[68:69], v[68:69], v[82:83] op_sel_hi:[1,0]
	v_ashrrev_i32_e32 v65, 31, v64
	global_store_dwordx4 v[80:81], v[76:79], off
	global_store_dwordx4 v[80:81], v[72:75], off offset:64
	global_store_dwordx4 v[80:81], v[68:71], off offset:512
	v_lshl_add_u64 v[66:67], v[64:65], 2, s[8:9]
	s_waitcnt vmcnt(19)
; #define PG8_BAR __builtin_amdgcn_s_barrier()
; template <class Epi, class Sched, bool ALIGN_EPI = false, bool SP2 = false>
; __device__ __forceinline__ void gemm_phase(PG8_LAS unsigned char* lds, const Gemm g, const Sched& S, const Epi& E) {
;     ...
;         if constexpr (ALIGN_EPI) { if (wr == 0) PG8_BAR; }
;         if constexpr (!Epi::AFTER_DRAIN) { E(acc, cur, wr, wc, fr, fq); S.done(cur); }
;         if (!has_next) break;
; #pragma unroll
;         for (int a = 0; a < 2; ++a)
; #pragma unroll
;             for (int b = 0; b < 2; ++b)
; #pragma unroll
;                 for (int m = 0; m < 4; ++m)
; #pragma unroll
;                     for (int n = 0; n < 2; ++n) acc[a][b][m][n] = (f32x4){0.f, 0.f, 0.f, 0.f};
;         cur = nxt; cA = nA; cB = nB; ++ui;
;         if constexpr (ALIGN_EPI) { if (wr == 1) PG8_BAR; }
;     __device__ __forceinline__ void operator()(const f32x4 (&acc)[2][2][4][2], const Unit& u, int wr, int wc, int fr, int fq) const {
;         const int col0 = u.pn * BM + wc * 32 + 4 * fq;
; #pragma unroll
;         for (int ai = 0; ai < 2; ++ai)
; #pragma unroll
;             for (int m = 0; m < 4; ++m) { const int row = u.pm * BM + ai * HALF + wr * 64 + m * 16 + fr; const size_t off = (size_t)row * ldc + col0;
;                 const float rs = rsqrtf(SS[row] * (1.f / 2048.f) + 1e-6f);
; #pragma unroll
;                 for (int bj = 0; bj < 2; ++bj)
; #pragma unroll
;                     for (int n = 0; n < 2; ++n) *(f32x4*)(O + off + bj * HALF + n * 16) = acc[ai][bj][m][n] * rs; }
	v_mov_b32_e32 v65, v203
	v_fmamk_f32 v65, v65, 0x3a000000, v173
	v_cmp_gt_f32_e32 vcc, s76, v65
	v_mul_f32_e32 v66, 0x4b800000, v65
	s_nop 0
	v_cndmask_b32_e32 v65, v65, v66, vcc
	v_rsq_f32_e32 v65, v65
	s_nop 0
	v_mul_f32_e32 v66, 0x45800000, v65
	v_cndmask_b32_e32 v66, v65, v66, vcc
	v_mad_i64_i32 v[64:65], s[0:1], v64, s14, v[124:125]
	v_lshl_add_u64 v[64:65], v[64:65], 0, v[126:127]
	v_pk_mul_f32 v[50:51], v[50:51], v[66:67] op_sel_hi:[1,0]
	v_pk_mul_f32 v[48:49], v[48:49], v[66:67] op_sel_hi:[1,0]
	global_store_dwordx4 v[64:65], v[48:51], off offset:576
	v_pk_mul_f32 v[62:63], v[62:63], v[66:67] op_sel_hi:[1,0]
	v_pk_mul_f32 v[60:61], v[60:61], v[66:67] op_sel_hi:[1,0]
	v_add_u32_e32 v48, 0x90, v136
	v_pk_mul_f32 v[58:59], v[58:59], v[66:67] op_sel_hi:[1,0]
	v_pk_mul_f32 v[56:57], v[56:57], v[66:67] op_sel_hi:[1,0]
	v_pk_mul_f32 v[54:55], v[54:55], v[66:67] op_sel_hi:[1,0]
	v_pk_mul_f32 v[52:53], v[52:53], v[66:67] op_sel_hi:[1,0]
	v_ashrrev_i32_e32 v49, 31, v48
	global_store_dwordx4 v[64:65], v[60:63], off
	global_store_dwordx4 v[64:65], v[56:59], off offset:64
	global_store_dwordx4 v[64:65], v[52:55], off offset:512
	v_lshl_add_u64 v[50:51], v[48:49], 2, s[8:9]
	s_waitcnt vmcnt(22)
	v_mov_b32_e32 v49, v204
	v_fmamk_f32 v49, v49, 0x3a000000, v173
	v_cmp_gt_f32_e32 vcc, s76, v49
	v_mul_f32_e32 v50, 0x4b800000, v49
	s_nop 0
	v_cndmask_b32_e32 v49, v49, v50, vcc
	v_rsq_f32_e32 v49, v49
	s_nop 0
	v_mul_f32_e32 v50, 0x45800000, v49
	v_cndmask_b32_e32 v50, v49, v50, vcc
	v_mad_i64_i32 v[48:49], s[0:1], v48, s14, v[124:125]
	v_lshl_add_u64 v[48:49], v[48:49], 0, v[126:127]
	v_pk_mul_f32 v[34:35], v[34:35], v[50:51] op_sel_hi:[1,0]
	v_pk_mul_f32 v[32:33], v[32:33], v[50:51] op_sel_hi:[1,0]
	global_store_dwordx4 v[48:49], v[32:35], off offset:576
	v_pk_mul_f32 v[46:47], v[46:47], v[50:51] op_sel_hi:[1,0]
	v_pk_mul_f32 v[44:45], v[44:45], v[50:51] op_sel_hi:[1,0]
	v_add_u32_e32 v32, 0xa0, v136
	v_pk_mul_f32 v[42:43], v[42:43], v[50:51] op_sel_hi:[1,0]
	v_pk_mul_f32 v[40:41], v[40:41], v[50:51] op_sel_hi:[1,0]
	v_pk_mul_f32 v[38:39], v[38:39], v[50:51] op_sel_hi:[1,0]
	v_pk_mul_f32 v[36:37], v[36:37], v[50:51] op_sel_hi:[1,0]
	v_ashrrev_i32_e32 v33, 31, v32
	global_store_dwordx4 v[48:49], v[44:47], off
	global_store_dwordx4 v[48:49], v[40:43], off offset:64
	global_store_dwordx4 v[48:49], v[36:39], off offset:512
	v_lshl_add_u64 v[34:35], v[32:33], 2, s[8:9]
	s_waitcnt vmcnt(25)
	v_mov_b32_e32 v33, v205
	v_fmamk_f32 v33, v33, 0x3a000000, v173
	v_cmp_gt_f32_e32 vcc, s76, v33
	v_mul_f32_e32 v34, 0x4b800000, v33
	s_nop 0
	v_cndmask_b32_e32 v33, v33, v34, vcc
	v_rsq_f32_e32 v33, v33
	s_nop 0
	v_mul_f32_e32 v34, 0x45800000, v33
	v_cndmask_b32_e32 v34, v33, v34, vcc
	v_mad_i64_i32 v[32:33], s[0:1], v32, s14, v[124:125]
	v_lshl_add_u64 v[32:33], v[32:33], 0, v[126:127]
	v_pk_mul_f32 v[18:19], v[18:19], v[34:35] op_sel_hi:[1,0]
	v_pk_mul_f32 v[16:17], v[16:17], v[34:35] op_sel_hi:[1,0]
	global_store_dwordx4 v[32:33], v[16:19], off offset:576
	v_pk_mul_f32 v[30:31], v[30:31], v[34:35] op_sel_hi:[1,0]
	v_pk_mul_f32 v[28:29], v[28:29], v[34:35] op_sel_hi:[1,0]
	v_add_u32_e32 v16, 0xb0, v136
	v_pk_mul_f32 v[26:27], v[26:27], v[34:35] op_sel_hi:[1,0]
	v_pk_mul_f32 v[24:25], v[24:25], v[34:35] op_sel_hi:[1,0]
	v_pk_mul_f32 v[22:23], v[22:23], v[34:35] op_sel_hi:[1,0]
	v_pk_mul_f32 v[20:21], v[20:21], v[34:35] op_sel_hi:[1,0]
	v_ashrrev_i32_e32 v17, 31, v16
	global_store_dwordx4 v[32:33], v[28:31], off
	global_store_dwordx4 v[32:33], v[24:27], off offset:64
	global_store_dwordx4 v[32:33], v[20:23], off offset:512
	v_lshl_add_u64 v[18:19], v[16:17], 2, s[8:9]
	s_waitcnt vmcnt(28)
	v_mov_b32_e32 v17, v206
	v_fmamk_f32 v17, v17, 0x3a000000, v173
	v_cmp_gt_f32_e32 vcc, s76, v17
	v_mul_f32_e32 v18, 0x4b800000, v17
	s_nop 0
	v_cndmask_b32_e32 v17, v17, v18, vcc
	v_rsq_f32_e32 v17, v17
	s_nop 0
	v_mul_f32_e32 v18, 0x45800000, v17
	v_cndmask_b32_e32 v18, v17, v18, vcc
	v_mad_i64_i32 v[16:17], s[0:1], v16, s14, v[124:125]
	v_pk_mul_f32 v[14:15], v[14:15], v[18:19] op_sel_hi:[1,0]
	v_pk_mul_f32 v[12:13], v[12:13], v[18:19] op_sel_hi:[1,0]
	v_lshl_add_u64 v[16:17], v[16:17], 0, v[126:127]
	v_pk_mul_f32 v[10:11], v[10:11], v[18:19] op_sel_hi:[1,0]
	v_pk_mul_f32 v[8:9], v[8:9], v[18:19] op_sel_hi:[1,0]
	v_pk_mul_f32 v[6:7], v[6:7], v[18:19] op_sel_hi:[1,0]
	v_pk_mul_f32 v[4:5], v[4:5], v[18:19] op_sel_hi:[1,0]
	v_pk_mul_f32 v[2:3], v[2:3], v[18:19] op_sel_hi:[1,0]
	v_pk_mul_f32 v[0:1], v[0:1], v[18:19] op_sel_hi:[1,0]
	s_mov_b64 s[0:1], -1
	s_andn2_b64 vcc, exec, s[38:39]
	global_store_dwordx4 v[16:17], v[12:15], off
	global_store_dwordx4 v[16:17], v[8:11], off offset:64
	global_store_dwordx4 v[16:17], v[4:7], off offset:512
	global_store_dwordx4 v[16:17], v[0:3], off offset:576
	s_cbranch_vccnz .LBB0_354
	s_andn2_b64 vcc, exec, s[4:5]
	s_cbranch_vccnz .LBB0_353
	s_barrier
	s_branch .LBB0_353

; __device__ __forceinline__ unsigned cvt_pk_bf16(float lo, float hi) { unsigned r; asm volatile("v_cvt_pk_bf16_f32 %0, %1, %2" : "=v"(r) : "v"(lo), "v"(hi)); return r; }
;     __device__ __forceinline__ void operator()(const f32x4 (&acc)[2][2][4][2], const Unit& u, int wr, int wc, int fr, int fq) const {
;         const int col0 = u.pn * BM + wc * 32 + 4 * fq;
;         f32x4 gv[2][2];
; #pragma unroll
;         for (int bj = 0; bj < 2; ++bj)
; #pragma unroll
;             for (int n = 0; n < 2; ++n) gv[bj][n] = gnext ? *(const f32x4*)(gnext + col0 + bj * HALF + n * 16) : (f32x4){0.f, 0.f, 0.f, 0.f};
; #pragma unroll
;         for (int ai = 0; ai < 2; ++ai)
; #pragma unroll
;             for (int m = 0; m < 4; ++m) { const int row = u.pm * BM + ai * HALF + wr * 64 + m * 16 + fr; const size_t off = (size_t)row * ldc + col0;
;                 float ssum = 0.f;
; #pragma unroll
;                 for (int bj = 0; bj < 2; ++bj)
; #pragma unroll
;                     for (int n = 0; n < 2; ++n) { f32x4* p = (f32x4*)(X + off + bj * HALF + n * 16); const f32x4 v = *(const f32x4*)(Xin + off + bj * HALF + n * 16) + acc[ai][bj][m][n] * scale; *p = v;
;                         if (gnext) { ssum += (v.x * v.x + v.y * v.y) + (v.z * v.z + v.w * v.w); const f32x4 o = v * gv[bj][n];
;                             u32x2 w; w.x = cvt_pk_bf16(o.x, o.y); w.y = cvt_pk_bf16(o.z, o.w); *(u32x2*)(XB + off + bj * HALF + n * 16) = w; } }
;                 if (gnext) { ssum += __shfl_xor(ssum, 16); ssum += __shfl_xor(ssum, 32); if (fq == 0) unsafeAtomicAdd(SS + row, ssum); } }
.LBB0_502:
	v_lshl_add_u32 v162, s61, 8, v145
	v_ashrrev_i32_e32 v163, 31, v162
	v_add_u32_e32 v194, 0x0, v162
	v_ashrrev_i32_e32 v195, 31, v194
	v_lshlrev_b64 v[194:195], 11, v[194:195]
	v_lshl_add_u64 v[194:195], v[194:195], 0, v[164:165]
	v_lshlrev_b64 v[194:195], 2, v[194:195]
	v_lshl_add_u64 v[194:195], s[6:7], 0, v[194:195]
	global_load_dwordx4 v[198:201], v[194:195], off
	global_load_dwordx4 v[202:205], v[194:195], off offset:64
	global_load_dwordx4 v[206:209], v[194:195], off offset:512
	global_load_dwordx4 v[210:213], v[194:195], off offset:576
	v_add_u32_e32 v196, 0x10, v162
	v_ashrrev_i32_e32 v197, 31, v196
	v_lshlrev_b64 v[196:197], 11, v[196:197]
	v_lshl_add_u64 v[196:197], v[196:197], 0, v[164:165]
	v_lshlrev_b64 v[196:197], 2, v[196:197]
	v_lshl_add_u64 v[196:197], s[6:7], 0, v[196:197]
	global_load_dwordx4 v[214:217], v[196:197], off
	global_load_dwordx4 v[218:221], v[196:197], off offset:64
	global_load_dwordx4 v[222:225], v[196:197], off offset:512
	global_load_dwordx4 v[226:229], v[196:197], off offset:576
	s_waitcnt vmcnt(0)
	v_lshlrev_b64 v[166:167], 11, v[162:163]
	v_lshl_add_u64 v[170:171], v[166:167], 0, v[164:165]
	v_lshlrev_b64 v[166:167], 2, v[170:171]
	v_lshl_add_u64 v[168:169], s[6:7], 0, v[166:167]
	s_nop 1
	v_mov_b64_e32 v[190:191], v[198:199]
	v_mov_b64_e32 v[192:193], v[200:201]
	v_mov_b32_e32 v155, v154
	v_lshl_add_u64 v[166:167], s[16:17], 0, v[166:167]
	s_and_b64 vcc, exec, s[42:43]
	v_pk_fma_f32 v[142:143], v[154:155], v[142:143], v[192:193]
	v_pk_fma_f32 v[140:141], v[156:157], v[140:141], v[190:191]
	global_store_dwordx4 v[166:167], v[140:143], off
	s_cbranch_vccnz .LBB0_545
	v_mul_f32_e32 v180, v141, v141
	v_fmac_f32_e32 v180, v140, v140
	v_mul_f32_e32 v181, v143, v143
	v_pk_mul_f32 v[140:141], v[56:57], v[140:141]
	v_lshl_add_u64 v[170:171], v[170:171], 1, s[10:11]
	v_fmac_f32_e32 v181, v142, v142
	v_pk_mul_f32 v[142:143], v[58:59], v[142:143]
	v_cvt_pk_bf16_f32 v140, v140, v141
	v_add_f32_e32 v180, v180, v181
	v_cvt_pk_bf16_f32 v141, v142, v143
	global_store_dwordx2 v[170:171], v[140:141], off
	s_nop 1
	v_mov_b64_e32 v[140:141], v[202:203]
	v_mov_b64_e32 v[142:143], v[204:205]
	v_pk_fma_f32 v[140:141], v[156:157], v[136:137], v[140:141]
	v_pk_fma_f32 v[142:143], v[154:155], v[138:139], v[142:143]
	v_mul_f32_e32 v181, v141, v141
	global_store_dwordx4 v[166:167], v[140:143], off offset:64
	v_fmac_f32_e32 v181, v140, v140
	v_mul_f32_e32 v182, v143, v143
	v_pk_mul_f32 v[140:141], v[48:49], v[140:141]
	v_fmac_f32_e32 v182, v142, v142
	v_pk_mul_f32 v[142:143], v[50:51], v[142:143]
	v_cvt_pk_bf16_f32 v140, v140, v141
	v_add_f32_e32 v181, v181, v182
	v_cvt_pk_bf16_f32 v141, v142, v143
	global_store_dwordx2 v[170:171], v[140:141], off offset:32
	s_nop 1
	v_mov_b64_e32 v[140:141], v[206:207]
	v_mov_b64_e32 v[142:143], v[208:209]
	v_add_f32_e32 v180, v180, v181
	v_pk_fma_f32 v[140:141], v[156:157], v[132:133], v[140:141]
	v_pk_fma_f32 v[142:143], v[154:155], v[134:135], v[142:143]
	v_mul_f32_e32 v181, v141, v141
	global_store_dwordx4 v[166:167], v[140:143], off offset:512
	v_fmac_f32_e32 v181, v140, v140
	v_mul_f32_e32 v182, v143, v143
	v_pk_mul_f32 v[140:141], v[52:53], v[140:141]
	v_fmac_f32_e32 v182, v142, v142
	v_pk_mul_f32 v[142:143], v[54:55], v[142:143]
	v_cvt_pk_bf16_f32 v140, v140, v141
	v_add_f32_e32 v181, v181, v182
	v_cvt_pk_bf16_f32 v141, v142, v143
	global_store_dwordx2 v[170:171], v[140:141], off offset:256
	s_nop 1
	v_mov_b64_e32 v[140:141], v[210:211]
	v_mov_b64_e32 v[142:143], v[212:213]
	v_add_f32_e32 v190, v180, v181
	v_pk_fma_f32 v[142:143], v[154:155], v[126:127], v[142:143]
	v_pk_fma_f32 v[140:141], v[156:157], v[124:125], v[140:141]
	global_store_dwordx4 v[166:167], v[140:143], off offset:576
	v_pk_mul_f32 v[182:183], v[44:45], v[140:141]
	v_pk_mul_f32 v[180:181], v[46:47], v[142:143]
	v_mul_f32_e32 v141, v141, v141
	v_fmac_f32_e32 v141, v140, v140
	v_mul_f32_e32 v140, v143, v143
	v_fmac_f32_e32 v140, v142, v142
	v_and_b32_e32 v142, 64, v176
	v_add_f32_e32 v140, v141, v140
	v_xor_b32_e32 v141, 16, v176
	v_add_u32_e32 v142, 64, v142
	v_cmp_lt_i32_e32 vcc, v141, v142
	v_add_f32_e32 v140, v190, v140
	v_cvt_pk_bf16_f32 v182, v182, v183
	v_cvt_pk_bf16_f32 v183, v180, v181
	global_store_dwordx2 v[170:171], v[182:183], off offset:288
	v_cndmask_b32_e32 v141, v176, v141, vcc
	v_lshlrev_b32_e32 v141, 2, v141
	ds_bpermute_b32 v141, v141, v140
	s_waitcnt lgkmcnt(0)
	v_add_f32_e32 v140, v140, v141
	v_xor_b32_e32 v141, 32, v176
	v_cmp_lt_i32_e32 vcc, v141, v142
	s_nop 1
	v_cndmask_b32_e32 v141, v176, v141, vcc
	v_lshlrev_b32_e32 v141, 2, v141
	ds_bpermute_b32 v141, v141, v140
	s_and_saveexec_b64 s[0:1], s[38:39]
	s_cbranch_execz .LBB0_505
	v_lshl_add_u64 v[142:143], v[162:163], 2, s[20:21]
	s_waitcnt lgkmcnt(0)
	v_add_f32_e32 v140, v140, v141
	global_atomic_add_f32 v[142:143], v140, off

; __device__ __forceinline__ unsigned cvt_pk_bf16(float lo, float hi) { unsigned r; asm volatile("v_cvt_pk_bf16_f32 %0, %1, %2" : "=v"(r) : "v"(lo), "v"(hi)); return r; }
;     __device__ __forceinline__ void operator()(const f32x4 (&acc)[2][2][4][2], const Unit& u, int wr, int wc, int fr, int fq) const {
;         const int col0 = u.pn * BM + wc * 32 + 4 * fq;
;         f32x4 gv[2][2];
; #pragma unroll
;         for (int bj = 0; bj < 2; ++bj)
; #pragma unroll
;             for (int n = 0; n < 2; ++n) gv[bj][n] = gnext ? *(const f32x4*)(gnext + col0 + bj * HALF + n * 16) : (f32x4){0.f, 0.f, 0.f, 0.f};
; #pragma unroll
;         for (int ai = 0; ai < 2; ++ai)
; #pragma unroll
;             for (int m = 0; m < 4; ++m) { const int row = u.pm * BM + ai * HALF + wr * 64 + m * 16 + fr; const size_t off = (size_t)row * ldc + col0;
;                 float ssum = 0.f;
; #pragma unroll
;                 for (int bj = 0; bj < 2; ++bj)
; #pragma unroll
;                     for (int n = 0; n < 2; ++n) { f32x4* p = (f32x4*)(X + off + bj * HALF + n * 16); const f32x4 v = *(const f32x4*)(Xin + off + bj * HALF + n * 16) + acc[ai][bj][m][n] * scale; *p = v;
;                         if (gnext) { ssum += (v.x * v.x + v.y * v.y) + (v.z * v.z + v.w * v.w); const f32x4 o = v * gv[bj][n];
;                             u32x2 w; w.x = cvt_pk_bf16(o.x, o.y); w.y = cvt_pk_bf16(o.z, o.w); *(u32x2*)(XB + off + bj * HALF + n * 16) = w; } }
;                 if (gnext) { ssum += __shfl_xor(ssum, 16); ssum += __shfl_xor(ssum, 32); if (fq == 0) unsafeAtomicAdd(SS + row, ssum); } }
.LBB0_506:
	s_waitcnt lgkmcnt(0)
	s_nop 1
	v_mov_b64_e32 v[140:141], v[202:203]
	v_mov_b64_e32 v[142:143], v[204:205]
	v_mov_b32_e32 v155, v154
	v_pk_fma_f32 v[138:139], v[154:155], v[138:139], v[142:143]
	v_pk_fma_f32 v[136:137], v[156:157], v[136:137], v[140:141]
	global_store_dwordx4 v[166:167], v[136:139], off offset:64
	s_nop 1
	v_mov_b64_e32 v[136:137], v[206:207]
	v_mov_b64_e32 v[138:139], v[208:209]
	v_pk_fma_f32 v[134:135], v[154:155], v[134:135], v[138:139]
	v_pk_fma_f32 v[132:133], v[156:157], v[132:133], v[136:137]
	global_store_dwordx4 v[166:167], v[132:135], off offset:512
	s_nop 1
	v_mov_b64_e32 v[132:133], v[210:211]
	v_mov_b64_e32 v[134:135], v[212:213]
	v_pk_fma_f32 v[126:127], v[154:155], v[126:127], v[134:135]
	v_pk_fma_f32 v[124:125], v[156:157], v[124:125], v[132:133]
	global_store_dwordx4 v[166:167], v[124:127], off offset:576
.LBB0_507:
	s_nop 1
	v_or_b32_e32 v124, 16, v162
	v_ashrrev_i32_e32 v125, 31, v124
	v_lshlrev_b64 v[124:125], 11, v[124:125]
	v_lshl_add_u64 v[136:137], v[124:125], 0, v[164:165]
	v_lshlrev_b64 v[132:133], 2, v[136:137]
	v_lshl_add_u64 v[134:135], s[6:7], 0, v[132:133]
	s_nop 1
	v_mov_b64_e32 v[124:125], v[214:215]
	v_mov_b64_e32 v[126:127], v[216:217]
	v_mov_b32_e32 v155, v154
	v_lshl_add_u64 v[132:133], s[16:17], 0, v[132:133]
	s_and_b64 vcc, exec, s[42:43]
	v_pk_fma_f32 v[126:127], v[154:155], v[130:131], v[126:127]
	v_pk_fma_f32 v[124:125], v[156:157], v[128:129], v[124:125]
	global_store_dwordx4 v[132:133], v[124:127], off
	s_cbranch_vccnz .LBB0_546
	v_mul_f32_e32 v128, v125, v125
	v_mul_f32_e32 v129, v127, v127
	v_fmac_f32_e32 v128, v124, v124
	v_fmac_f32_e32 v129, v126, v126
	v_add_f32_e32 v130, v128, v129
	v_pk_mul_f32 v[124:125], v[56:57], v[124:125]
	v_lshl_add_u64 v[128:129], v[136:137], 1, s[10:11]
	v_pk_mul_f32 v[126:127], v[58:59], v[126:127]
	v_cvt_pk_bf16_f32 v124, v124, v125
	s_nop 0
	v_cvt_pk_bf16_f32 v125, v126, v127
	global_store_dwordx2 v[128:129], v[124:125], off
	s_nop 1
	v_mov_b64_e32 v[124:125], v[218:219]
	v_mov_b64_e32 v[126:127], v[220:221]
	v_pk_fma_f32 v[124:125], v[156:157], v[120:121], v[124:125]
	v_pk_fma_f32 v[126:127], v[154:155], v[122:123], v[126:127]
	v_mul_f32_e32 v131, v125, v125
	global_store_dwordx4 v[132:133], v[124:127], off offset:64
	v_fmac_f32_e32 v131, v124, v124
	v_mul_f32_e32 v136, v127, v127
	v_pk_mul_f32 v[124:125], v[48:49], v[124:125]
	v_fmac_f32_e32 v136, v126, v126
	v_pk_mul_f32 v[126:127], v[50:51], v[126:127]
	v_cvt_pk_bf16_f32 v124, v124, v125
	v_add_f32_e32 v131, v131, v136
	v_cvt_pk_bf16_f32 v125, v126, v127
	global_store_dwordx2 v[128:129], v[124:125], off offset:32
	s_nop 1
	v_mov_b64_e32 v[124:125], v[222:223]
	v_mov_b64_e32 v[126:127], v[224:225]
	v_add_f32_e32 v130, v130, v131
	v_pk_fma_f32 v[124:125], v[156:157], v[116:117], v[124:125]
	v_pk_fma_f32 v[126:127], v[154:155], v[118:119], v[126:127]
	v_mul_f32_e32 v131, v125, v125
	global_store_dwordx4 v[132:133], v[124:127], off offset:512
	v_fmac_f32_e32 v131, v124, v124
	v_mul_f32_e32 v136, v127, v127
	v_pk_mul_f32 v[124:125], v[52:53], v[124:125]
	v_fmac_f32_e32 v136, v126, v126
	v_pk_mul_f32 v[126:127], v[54:55], v[126:127]
	v_cvt_pk_bf16_f32 v124, v124, v125
	v_add_f32_e32 v131, v131, v136
	v_cvt_pk_bf16_f32 v125, v126, v127
	global_store_dwordx2 v[128:129], v[124:125], off offset:256
	s_nop 1
	v_mov_b64_e32 v[124:125], v[226:227]
	v_mov_b64_e32 v[126:127], v[228:229]
	v_add_f32_e32 v138, v130, v131
	v_pk_fma_f32 v[126:127], v[154:155], v[110:111], v[126:127]
	v_pk_fma_f32 v[124:125], v[156:157], v[108:109], v[124:125]
	global_store_dwordx4 v[132:133], v[124:127], off offset:576
	v_pk_mul_f32 v[136:137], v[44:45], v[124:125]
	v_pk_mul_f32 v[130:131], v[46:47], v[126:127]
	v_mul_f32_e32 v125, v125, v125
	v_fmac_f32_e32 v125, v124, v124
	v_mul_f32_e32 v124, v127, v127
	v_fmac_f32_e32 v124, v126, v126
	v_and_b32_e32 v126, 64, v176
	v_add_f32_e32 v124, v125, v124
	v_xor_b32_e32 v125, 16, v176
	v_add_u32_e32 v126, 64, v126
	v_cmp_lt_i32_e32 vcc, v125, v126
	v_add_f32_e32 v124, v138, v124
	v_cvt_pk_bf16_f32 v136, v136, v137
	v_cvt_pk_bf16_f32 v137, v130, v131
	global_store_dwordx2 v[128:129], v[136:137], off offset:288
	v_cndmask_b32_e32 v125, v176, v125, vcc
	v_lshlrev_b32_e32 v125, 2, v125
	ds_bpermute_b32 v125, v125, v124
	s_waitcnt lgkmcnt(0)
	v_add_f32_e32 v124, v124, v125
	v_xor_b32_e32 v125, 32, v176
	v_cmp_lt_i32_e32 vcc, v125, v126
	s_nop 1
	v_cndmask_b32_e32 v125, v176, v125, vcc
	v_lshlrev_b32_e32 v125, 2, v125
	ds_bpermute_b32 v125, v125, v124
	s_and_saveexec_b64 s[0:1], s[38:39]
	s_cbranch_execz .LBB0_510
	v_lshl_add_u64 v[126:127], v[162:163], 2, s[20:21]
	s_waitcnt lgkmcnt(0)
	v_add_f32_e32 v124, v124, v125
	global_atomic_add_f32 v[126:127], v124, off offset:64

; __device__ __forceinline__ unsigned cvt_pk_bf16(float lo, float hi) { unsigned r; asm volatile("v_cvt_pk_bf16_f32 %0, %1, %2" : "=v"(r) : "v"(lo), "v"(hi)); return r; }
;     __device__ __forceinline__ void operator()(const f32x4 (&acc)[2][2][4][2], const Unit& u, int wr, int wc, int fr, int fq) const {
;         const int col0 = u.pn * BM + wc * 32 + 4 * fq;
;         f32x4 gv[2][2];
; #pragma unroll
;         for (int bj = 0; bj < 2; ++bj)
; #pragma unroll
;             for (int n = 0; n < 2; ++n) gv[bj][n] = gnext ? *(const f32x4*)(gnext + col0 + bj * HALF + n * 16) : (f32x4){0.f, 0.f, 0.f, 0.f};
; #pragma unroll
;         for (int ai = 0; ai < 2; ++ai)
; #pragma unroll
;             for (int m = 0; m < 4; ++m) { const int row = u.pm * BM + ai * HALF + wr * 64 + m * 16 + fr; const size_t off = (size_t)row * ldc + col0;
;                 float ssum = 0.f;
; #pragma unroll
;                 for (int bj = 0; bj < 2; ++bj)
; #pragma unroll
;                     for (int n = 0; n < 2; ++n) { f32x4* p = (f32x4*)(X + off + bj * HALF + n * 16); const f32x4 v = *(const f32x4*)(Xin + off + bj * HALF + n * 16) + acc[ai][bj][m][n] * scale; *p = v;
;                         if (gnext) { ssum += (v.x * v.x + v.y * v.y) + (v.z * v.z + v.w * v.w); const f32x4 o = v * gv[bj][n];
;                             u32x2 w; w.x = cvt_pk_bf16(o.x, o.y); w.y = cvt_pk_bf16(o.z, o.w); *(u32x2*)(XB + off + bj * HALF + n * 16) = w; } }
;                 if (gnext) { ssum += __shfl_xor(ssum, 16); ssum += __shfl_xor(ssum, 32); if (fq == 0) unsafeAtomicAdd(SS + row, ssum); } }
.LBB0_511:
	s_waitcnt lgkmcnt(0)
	s_nop 1
	v_mov_b64_e32 v[124:125], v[218:219]
	v_mov_b64_e32 v[126:127], v[220:221]
	v_mov_b32_e32 v155, v154
	v_pk_fma_f32 v[122:123], v[154:155], v[122:123], v[126:127]
	v_pk_fma_f32 v[120:121], v[156:157], v[120:121], v[124:125]
	global_store_dwordx4 v[132:133], v[120:123], off offset:64
	s_nop 1
	v_mov_b64_e32 v[120:121], v[222:223]
	v_mov_b64_e32 v[122:123], v[224:225]
	v_pk_fma_f32 v[118:119], v[154:155], v[118:119], v[122:123]
	v_pk_fma_f32 v[116:117], v[156:157], v[116:117], v[120:121]
	global_store_dwordx4 v[132:133], v[116:119], off offset:512
	s_nop 1
	v_mov_b64_e32 v[116:117], v[226:227]
	v_mov_b64_e32 v[118:119], v[228:229]
	v_pk_fma_f32 v[110:111], v[154:155], v[110:111], v[118:119]
	v_pk_fma_f32 v[108:109], v[156:157], v[108:109], v[116:117]
	global_store_dwordx4 v[132:133], v[108:111], off offset:576
.LBB0_512:
	s_nop 1
	v_add_u32_e32 v194, 0x20, v162
	v_ashrrev_i32_e32 v195, 31, v194
	v_lshlrev_b64 v[194:195], 11, v[194:195]
	v_lshl_add_u64 v[194:195], v[194:195], 0, v[164:165]
	v_lshlrev_b64 v[194:195], 2, v[194:195]
	v_lshl_add_u64 v[194:195], s[6:7], 0, v[194:195]
	global_load_dwordx4 v[198:201], v[194:195], off
	global_load_dwordx4 v[202:205], v[194:195], off offset:64
	global_load_dwordx4 v[206:209], v[194:195], off offset:512
	global_load_dwordx4 v[210:213], v[194:195], off offset:576
	v_add_u32_e32 v196, 0x30, v162
	v_ashrrev_i32_e32 v197, 31, v196
	v_lshlrev_b64 v[196:197], 11, v[196:197]
	v_lshl_add_u64 v[196:197], v[196:197], 0, v[164:165]
	v_lshlrev_b64 v[196:197], 2, v[196:197]
	v_lshl_add_u64 v[196:197], s[6:7], 0, v[196:197]
	global_load_dwordx4 v[214:217], v[196:197], off
	global_load_dwordx4 v[218:221], v[196:197], off offset:64
	global_load_dwordx4 v[222:225], v[196:197], off offset:512
	global_load_dwordx4 v[226:229], v[196:197], off offset:576
	s_waitcnt vmcnt(0)
	v_or_b32_e32 v108, 32, v162
	v_ashrrev_i32_e32 v109, 31, v108
	v_lshlrev_b64 v[108:109], 11, v[108:109]
	v_lshl_add_u64 v[120:121], v[108:109], 0, v[164:165]
	v_lshlrev_b64 v[116:117], 2, v[120:121]
	v_lshl_add_u64 v[118:119], s[6:7], 0, v[116:117]
	s_nop 1
	v_mov_b64_e32 v[108:109], v[198:199]
	v_mov_b64_e32 v[110:111], v[200:201]
	v_mov_b32_e32 v155, v154
	v_lshl_add_u64 v[116:117], s[16:17], 0, v[116:117]
	s_and_b64 vcc, exec, s[42:43]
	v_pk_fma_f32 v[110:111], v[154:155], v[114:115], v[110:111]
	v_pk_fma_f32 v[108:109], v[156:157], v[112:113], v[108:109]
	global_store_dwordx4 v[116:117], v[108:111], off
	s_cbranch_vccnz .LBB0_547
	v_mul_f32_e32 v112, v109, v109
	v_mul_f32_e32 v113, v111, v111
	v_fmac_f32_e32 v112, v108, v108
	v_fmac_f32_e32 v113, v110, v110
	v_add_f32_e32 v114, v112, v113
	v_pk_mul_f32 v[108:109], v[56:57], v[108:109]
	v_lshl_add_u64 v[112:113], v[120:121], 1, s[10:11]
	v_pk_mul_f32 v[110:111], v[58:59], v[110:111]
	v_cvt_pk_bf16_f32 v108, v108, v109
	s_nop 0
	v_cvt_pk_bf16_f32 v109, v110, v111
	global_store_dwordx2 v[112:113], v[108:109], off
	s_nop 1
	v_mov_b64_e32 v[108:109], v[202:203]
	v_mov_b64_e32 v[110:111], v[204:205]
	v_pk_fma_f32 v[108:109], v[156:157], v[104:105], v[108:109]
	v_pk_fma_f32 v[110:111], v[154:155], v[106:107], v[110:111]
	v_mul_f32_e32 v115, v109, v109
	global_store_dwordx4 v[116:117], v[108:111], off offset:64
	v_fmac_f32_e32 v115, v108, v108
	v_mul_f32_e32 v120, v111, v111
	v_pk_mul_f32 v[108:109], v[48:49], v[108:109]
	v_fmac_f32_e32 v120, v110, v110
	v_pk_mul_f32 v[110:111], v[50:51], v[110:111]
	v_cvt_pk_bf16_f32 v108, v108, v109
	v_add_f32_e32 v115, v115, v120
	v_cvt_pk_bf16_f32 v109, v110, v111
	global_store_dwordx2 v[112:113], v[108:109], off offset:32
	s_nop 1
	v_mov_b64_e32 v[108:109], v[206:207]
	v_mov_b64_e32 v[110:111], v[208:209]
	v_add_f32_e32 v114, v114, v115
	v_pk_fma_f32 v[108:109], v[156:157], v[100:101], v[108:109]
	v_pk_fma_f32 v[110:111], v[154:155], v[102:103], v[110:111]
	v_mul_f32_e32 v115, v109, v109
	global_store_dwordx4 v[116:117], v[108:111], off offset:512
	v_fmac_f32_e32 v115, v108, v108
	v_mul_f32_e32 v120, v111, v111
	v_pk_mul_f32 v[108:109], v[52:53], v[108:109]
	v_fmac_f32_e32 v120, v110, v110
	v_pk_mul_f32 v[110:111], v[54:55], v[110:111]
	v_cvt_pk_bf16_f32 v108, v108, v109
	v_add_f32_e32 v115, v115, v120
	v_cvt_pk_bf16_f32 v109, v110, v111
	global_store_dwordx2 v[112:113], v[108:109], off offset:256
	s_nop 1
	v_mov_b64_e32 v[108:109], v[210:211]
	v_mov_b64_e32 v[110:111], v[212:213]
	v_add_f32_e32 v122, v114, v115
	v_pk_fma_f32 v[110:111], v[154:155], v[94:95], v[110:111]
	v_pk_fma_f32 v[108:109], v[156:157], v[92:93], v[108:109]
	global_store_dwordx4 v[116:117], v[108:111], off offset:576
	v_pk_mul_f32 v[120:121], v[44:45], v[108:109]
	v_pk_mul_f32 v[114:115], v[46:47], v[110:111]
	v_mul_f32_e32 v109, v109, v109
	v_fmac_f32_e32 v109, v108, v108
	v_mul_f32_e32 v108, v111, v111
	v_fmac_f32_e32 v108, v110, v110
	v_and_b32_e32 v110, 64, v176
	v_add_f32_e32 v108, v109, v108
	v_xor_b32_e32 v109, 16, v176
	v_add_u32_e32 v110, 64, v110
	v_cmp_lt_i32_e32 vcc, v109, v110
	v_add_f32_e32 v108, v122, v108
	v_cvt_pk_bf16_f32 v120, v120, v121
	v_cvt_pk_bf16_f32 v121, v114, v115
	global_store_dwordx2 v[112:113], v[120:121], off offset:288
	v_cndmask_b32_e32 v109, v176, v109, vcc
	v_lshlrev_b32_e32 v109, 2, v109
	ds_bpermute_b32 v109, v109, v108
	s_waitcnt lgkmcnt(0)
	v_add_f32_e32 v108, v108, v109
	v_xor_b32_e32 v109, 32, v176
	v_cmp_lt_i32_e32 vcc, v109, v110
	s_nop 1
	v_cndmask_b32_e32 v109, v176, v109, vcc
	v_lshlrev_b32_e32 v109, 2, v109
	ds_bpermute_b32 v109, v109, v108
	s_and_saveexec_b64 s[0:1], s[38:39]
	s_cbranch_execz .LBB0_515
	v_lshl_add_u64 v[110:111], v[162:163], 2, s[20:21]
	s_waitcnt lgkmcnt(0)
	v_add_f32_e32 v108, v108, v109
	global_atomic_add_f32 v[110:111], v108, off offset:128

; __device__ __forceinline__ unsigned cvt_pk_bf16(float lo, float hi) { unsigned r; asm volatile("v_cvt_pk_bf16_f32 %0, %1, %2" : "=v"(r) : "v"(lo), "v"(hi)); return r; }
;     __device__ __forceinline__ void operator()(const f32x4 (&acc)[2][2][4][2], const Unit& u, int wr, int wc, int fr, int fq) const {
;         const int col0 = u.pn * BM + wc * 32 + 4 * fq;
;         f32x4 gv[2][2];
; #pragma unroll
;         for (int bj = 0; bj < 2; ++bj)
; #pragma unroll
;             for (int n = 0; n < 2; ++n) gv[bj][n] = gnext ? *(const f32x4*)(gnext + col0 + bj * HALF + n * 16) : (f32x4){0.f, 0.f, 0.f, 0.f};
; #pragma unroll
;         for (int ai = 0; ai < 2; ++ai)
; #pragma unroll
;             for (int m = 0; m < 4; ++m) { const int row = u.pm * BM + ai * HALF + wr * 64 + m * 16 + fr; const size_t off = (size_t)row * ldc + col0;
;                 float ssum = 0.f;
; #pragma unroll
;                 for (int bj = 0; bj < 2; ++bj)
; #pragma unroll
;                     for (int n = 0; n < 2; ++n) { f32x4* p = (f32x4*)(X + off + bj * HALF + n * 16); const f32x4 v = *(const f32x4*)(Xin + off + bj * HALF + n * 16) + acc[ai][bj][m][n] * scale; *p = v;
;                         if (gnext) { ssum += (v.x * v.x + v.y * v.y) + (v.z * v.z + v.w * v.w); const f32x4 o = v * gv[bj][n];
;                             u32x2 w; w.x = cvt_pk_bf16(o.x, o.y); w.y = cvt_pk_bf16(o.z, o.w); *(u32x2*)(XB + off + bj * HALF + n * 16) = w; } }
;                 if (gnext) { ssum += __shfl_xor(ssum, 16); ssum += __shfl_xor(ssum, 32); if (fq == 0) unsafeAtomicAdd(SS + row, ssum); } }
.LBB0_516:
	s_waitcnt lgkmcnt(0)
	s_nop 1
	v_mov_b64_e32 v[108:109], v[202:203]
	v_mov_b64_e32 v[110:111], v[204:205]
	v_mov_b32_e32 v155, v154
	v_pk_fma_f32 v[106:107], v[154:155], v[106:107], v[110:111]
	v_pk_fma_f32 v[104:105], v[156:157], v[104:105], v[108:109]
	global_store_dwordx4 v[116:117], v[104:107], off offset:64
	s_nop 1
	v_mov_b64_e32 v[104:105], v[206:207]
	v_mov_b64_e32 v[106:107], v[208:209]
	v_pk_fma_f32 v[102:103], v[154:155], v[102:103], v[106:107]
	v_pk_fma_f32 v[100:101], v[156:157], v[100:101], v[104:105]
	global_store_dwordx4 v[116:117], v[100:103], off offset:512
	s_nop 1
	v_mov_b64_e32 v[100:101], v[210:211]
	v_mov_b64_e32 v[102:103], v[212:213]
	v_pk_fma_f32 v[94:95], v[154:155], v[94:95], v[102:103]
	v_pk_fma_f32 v[92:93], v[156:157], v[92:93], v[100:101]
	global_store_dwordx4 v[116:117], v[92:95], off offset:576
.LBB0_517:
	s_nop 1
	v_or_b32_e32 v92, 48, v162
	v_ashrrev_i32_e32 v93, 31, v92
	v_lshlrev_b64 v[92:93], 11, v[92:93]
	v_lshl_add_u64 v[104:105], v[92:93], 0, v[164:165]
	v_lshlrev_b64 v[100:101], 2, v[104:105]
	v_lshl_add_u64 v[102:103], s[6:7], 0, v[100:101]
	s_nop 1
	v_mov_b64_e32 v[92:93], v[214:215]
	v_mov_b64_e32 v[94:95], v[216:217]
	v_mov_b32_e32 v155, v154
	v_lshl_add_u64 v[100:101], s[16:17], 0, v[100:101]
	s_and_b64 vcc, exec, s[42:43]
	v_pk_fma_f32 v[94:95], v[154:155], v[98:99], v[94:95]
	v_pk_fma_f32 v[92:93], v[156:157], v[96:97], v[92:93]
	global_store_dwordx4 v[100:101], v[92:95], off
	s_cbranch_vccnz .LBB0_548
	v_mul_f32_e32 v96, v93, v93
	v_mul_f32_e32 v97, v95, v95
	v_fmac_f32_e32 v96, v92, v92
	v_fmac_f32_e32 v97, v94, v94
	v_add_f32_e32 v98, v96, v97
	v_pk_mul_f32 v[92:93], v[56:57], v[92:93]
	v_lshl_add_u64 v[96:97], v[104:105], 1, s[10:11]
	v_pk_mul_f32 v[94:95], v[58:59], v[94:95]
	v_cvt_pk_bf16_f32 v92, v92, v93
	s_nop 0
	v_cvt_pk_bf16_f32 v93, v94, v95
	global_store_dwordx2 v[96:97], v[92:93], off
	s_nop 1
	v_mov_b64_e32 v[92:93], v[218:219]
	v_mov_b64_e32 v[94:95], v[220:221]
	v_pk_fma_f32 v[92:93], v[156:157], v[88:89], v[92:93]
	v_pk_fma_f32 v[94:95], v[154:155], v[90:91], v[94:95]
	v_mul_f32_e32 v99, v93, v93
	global_store_dwordx4 v[100:101], v[92:95], off offset:64
	v_fmac_f32_e32 v99, v92, v92
	v_mul_f32_e32 v104, v95, v95
	v_pk_mul_f32 v[92:93], v[48:49], v[92:93]
	v_fmac_f32_e32 v104, v94, v94
	v_pk_mul_f32 v[94:95], v[50:51], v[94:95]
	v_cvt_pk_bf16_f32 v92, v92, v93
	v_add_f32_e32 v99, v99, v104
	v_cvt_pk_bf16_f32 v93, v94, v95
	global_store_dwordx2 v[96:97], v[92:93], off offset:32
	s_nop 1
	v_mov_b64_e32 v[92:93], v[222:223]
	v_mov_b64_e32 v[94:95], v[224:225]
	v_add_f32_e32 v98, v98, v99
	v_pk_fma_f32 v[92:93], v[156:157], v[84:85], v[92:93]
	v_pk_fma_f32 v[94:95], v[154:155], v[86:87], v[94:95]
	v_mul_f32_e32 v99, v93, v93
	global_store_dwordx4 v[100:101], v[92:95], off offset:512
	v_fmac_f32_e32 v99, v92, v92
	v_mul_f32_e32 v104, v95, v95
	v_pk_mul_f32 v[92:93], v[52:53], v[92:93]
	v_fmac_f32_e32 v104, v94, v94
	v_pk_mul_f32 v[94:95], v[54:55], v[94:95]
	v_cvt_pk_bf16_f32 v92, v92, v93
	v_add_f32_e32 v99, v99, v104
	v_cvt_pk_bf16_f32 v93, v94, v95
	global_store_dwordx2 v[96:97], v[92:93], off offset:256
	s_nop 1
	v_mov_b64_e32 v[92:93], v[226:227]
	v_mov_b64_e32 v[94:95], v[228:229]
	v_add_f32_e32 v106, v98, v99
	v_pk_fma_f32 v[94:95], v[154:155], v[82:83], v[94:95]
	v_pk_fma_f32 v[92:93], v[156:157], v[80:81], v[92:93]
	global_store_dwordx4 v[100:101], v[92:95], off offset:576
	v_pk_mul_f32 v[104:105], v[44:45], v[92:93]
	v_pk_mul_f32 v[98:99], v[46:47], v[94:95]
	v_mul_f32_e32 v93, v93, v93
	v_fmac_f32_e32 v93, v92, v92
	v_mul_f32_e32 v92, v95, v95
	v_fmac_f32_e32 v92, v94, v94
	v_and_b32_e32 v94, 64, v176
	v_add_f32_e32 v92, v93, v92
	v_xor_b32_e32 v93, 16, v176
	v_add_u32_e32 v94, 64, v94
	v_cmp_lt_i32_e32 vcc, v93, v94
	v_add_f32_e32 v92, v106, v92
	v_cvt_pk_bf16_f32 v104, v104, v105
	v_cvt_pk_bf16_f32 v105, v98, v99
	global_store_dwordx2 v[96:97], v[104:105], off offset:288
	v_cndmask_b32_e32 v93, v176, v93, vcc
	v_lshlrev_b32_e32 v93, 2, v93
	ds_bpermute_b32 v93, v93, v92
	s_waitcnt lgkmcnt(0)
	v_add_f32_e32 v92, v92, v93
	v_xor_b32_e32 v93, 32, v176
	v_cmp_lt_i32_e32 vcc, v93, v94
	s_nop 1
	v_cndmask_b32_e32 v93, v176, v93, vcc
	v_lshlrev_b32_e32 v93, 2, v93
	ds_bpermute_b32 v93, v93, v92
	s_and_saveexec_b64 s[0:1], s[38:39]
	s_cbranch_execz .LBB0_520
	v_lshl_add_u64 v[94:95], v[162:163], 2, s[20:21]
	s_waitcnt lgkmcnt(0)
	v_add_f32_e32 v92, v92, v93
	global_atomic_add_f32 v[94:95], v92, off offset:192

; __device__ __forceinline__ unsigned cvt_pk_bf16(float lo, float hi) { unsigned r; asm volatile("v_cvt_pk_bf16_f32 %0, %1, %2" : "=v"(r) : "v"(lo), "v"(hi)); return r; }
;     __device__ __forceinline__ void operator()(const f32x4 (&acc)[2][2][4][2], const Unit& u, int wr, int wc, int fr, int fq) const {
;         const int col0 = u.pn * BM + wc * 32 + 4 * fq;
;         f32x4 gv[2][2];
; #pragma unroll
;         for (int bj = 0; bj < 2; ++bj)
; #pragma unroll
;             for (int n = 0; n < 2; ++n) gv[bj][n] = gnext ? *(const f32x4*)(gnext + col0 + bj * HALF + n * 16) : (f32x4){0.f, 0.f, 0.f, 0.f};
; #pragma unroll
;         for (int ai = 0; ai < 2; ++ai)
; #pragma unroll
;             for (int m = 0; m < 4; ++m) { const int row = u.pm * BM + ai * HALF + wr * 64 + m * 16 + fr; const size_t off = (size_t)row * ldc + col0;
;                 float ssum = 0.f;
; #pragma unroll
;                 for (int bj = 0; bj < 2; ++bj)
; #pragma unroll
;                     for (int n = 0; n < 2; ++n) { f32x4* p = (f32x4*)(X + off + bj * HALF + n * 16); const f32x4 v = *(const f32x4*)(Xin + off + bj * HALF + n * 16) + acc[ai][bj][m][n] * scale; *p = v;
;                         if (gnext) { ssum += (v.x * v.x + v.y * v.y) + (v.z * v.z + v.w * v.w); const f32x4 o = v * gv[bj][n];
;                             u32x2 w; w.x = cvt_pk_bf16(o.x, o.y); w.y = cvt_pk_bf16(o.z, o.w); *(u32x2*)(XB + off + bj * HALF + n * 16) = w; } }
;                 if (gnext) { ssum += __shfl_xor(ssum, 16); ssum += __shfl_xor(ssum, 32); if (fq == 0) unsafeAtomicAdd(SS + row, ssum); } }
.LBB0_521:
	s_waitcnt lgkmcnt(0)
	s_nop 1
	v_mov_b64_e32 v[92:93], v[218:219]
	v_mov_b64_e32 v[94:95], v[220:221]
	v_mov_b32_e32 v155, v154
	v_pk_fma_f32 v[90:91], v[154:155], v[90:91], v[94:95]
	v_pk_fma_f32 v[88:89], v[156:157], v[88:89], v[92:93]
	global_store_dwordx4 v[100:101], v[88:91], off offset:64
	s_nop 1
	v_mov_b64_e32 v[88:89], v[222:223]
	v_mov_b64_e32 v[90:91], v[224:225]
	v_pk_fma_f32 v[86:87], v[154:155], v[86:87], v[90:91]
	v_pk_fma_f32 v[84:85], v[156:157], v[84:85], v[88:89]
	global_store_dwordx4 v[100:101], v[84:87], off offset:512
	s_nop 1
	v_mov_b64_e32 v[84:85], v[226:227]
	v_mov_b64_e32 v[86:87], v[228:229]
	v_pk_fma_f32 v[82:83], v[154:155], v[82:83], v[86:87]
	v_pk_fma_f32 v[80:81], v[156:157], v[80:81], v[84:85]
	global_store_dwordx4 v[100:101], v[80:83], off offset:576
.LBB0_522:
	s_nop 1
	v_add_u32_e32 v194, 0x80, v162
	v_ashrrev_i32_e32 v195, 31, v194
	v_lshlrev_b64 v[194:195], 11, v[194:195]
	v_lshl_add_u64 v[194:195], v[194:195], 0, v[164:165]
	v_lshlrev_b64 v[194:195], 2, v[194:195]
	v_lshl_add_u64 v[194:195], s[6:7], 0, v[194:195]
	global_load_dwordx4 v[198:201], v[194:195], off
	global_load_dwordx4 v[202:205], v[194:195], off offset:64
	global_load_dwordx4 v[206:209], v[194:195], off offset:512
	global_load_dwordx4 v[210:213], v[194:195], off offset:576
	v_add_u32_e32 v196, 0x90, v162
	v_ashrrev_i32_e32 v197, 31, v196
	v_lshlrev_b64 v[196:197], 11, v[196:197]
	v_lshl_add_u64 v[196:197], v[196:197], 0, v[164:165]
	v_lshlrev_b64 v[196:197], 2, v[196:197]
	v_lshl_add_u64 v[196:197], s[6:7], 0, v[196:197]
	global_load_dwordx4 v[214:217], v[196:197], off
	global_load_dwordx4 v[218:221], v[196:197], off offset:64
	global_load_dwordx4 v[222:225], v[196:197], off offset:512
	global_load_dwordx4 v[226:229], v[196:197], off offset:576
	s_waitcnt vmcnt(0)
	v_add_u32_e32 v80, 0x80, v162
	v_ashrrev_i32_e32 v81, 31, v80
	v_lshlrev_b64 v[80:81], 11, v[80:81]
	v_lshl_add_u64 v[84:85], v[80:81], 0, v[164:165]
	v_lshlrev_b64 v[80:81], 2, v[84:85]
	v_lshl_add_u64 v[82:83], s[6:7], 0, v[80:81]
	s_nop 1
	v_mov_b64_e32 v[86:87], v[198:199]
	v_mov_b64_e32 v[88:89], v[200:201]
	v_mov_b32_e32 v155, v154
	v_lshl_add_u64 v[80:81], s[16:17], 0, v[80:81]
	s_and_b64 vcc, exec, s[42:43]
	v_pk_fma_f32 v[78:79], v[154:155], v[78:79], v[88:89]
	v_pk_fma_f32 v[76:77], v[156:157], v[76:77], v[86:87]
	global_store_dwordx4 v[80:81], v[76:79], off
	s_cbranch_vccnz .LBB0_549
	v_mul_f32_e32 v86, v77, v77
	v_fmac_f32_e32 v86, v76, v76
	v_mul_f32_e32 v87, v79, v79
	v_pk_mul_f32 v[76:77], v[56:57], v[76:77]
	v_lshl_add_u64 v[84:85], v[84:85], 1, s[10:11]
	v_fmac_f32_e32 v87, v78, v78
	v_pk_mul_f32 v[78:79], v[58:59], v[78:79]
	v_cvt_pk_bf16_f32 v76, v76, v77
	v_add_f32_e32 v86, v86, v87
	v_cvt_pk_bf16_f32 v77, v78, v79
	global_store_dwordx2 v[84:85], v[76:77], off
	s_nop 1
	v_mov_b64_e32 v[76:77], v[202:203]
	v_mov_b64_e32 v[78:79], v[204:205]
	v_pk_fma_f32 v[76:77], v[156:157], v[72:73], v[76:77]
	v_pk_fma_f32 v[78:79], v[154:155], v[74:75], v[78:79]
	v_mul_f32_e32 v87, v77, v77
	global_store_dwordx4 v[80:81], v[76:79], off offset:64
	v_fmac_f32_e32 v87, v76, v76
	v_mul_f32_e32 v88, v79, v79
	v_pk_mul_f32 v[76:77], v[48:49], v[76:77]
	v_fmac_f32_e32 v88, v78, v78
	v_pk_mul_f32 v[78:79], v[50:51], v[78:79]
	v_cvt_pk_bf16_f32 v76, v76, v77
	v_add_f32_e32 v87, v87, v88
	v_cvt_pk_bf16_f32 v77, v78, v79
	global_store_dwordx2 v[84:85], v[76:77], off offset:32
	s_nop 1
	v_mov_b64_e32 v[76:77], v[206:207]
	v_mov_b64_e32 v[78:79], v[208:209]
	v_add_f32_e32 v86, v86, v87
	v_pk_fma_f32 v[76:77], v[156:157], v[68:69], v[76:77]
	v_pk_fma_f32 v[78:79], v[154:155], v[70:71], v[78:79]
	v_mul_f32_e32 v87, v77, v77
	global_store_dwordx4 v[80:81], v[76:79], off offset:512
	v_fmac_f32_e32 v87, v76, v76
	v_mul_f32_e32 v88, v79, v79
	v_pk_mul_f32 v[76:77], v[52:53], v[76:77]
	v_fmac_f32_e32 v88, v78, v78
	v_pk_mul_f32 v[78:79], v[54:55], v[78:79]
	v_cvt_pk_bf16_f32 v76, v76, v77
	v_add_f32_e32 v87, v87, v88
	v_cvt_pk_bf16_f32 v77, v78, v79
	global_store_dwordx2 v[84:85], v[76:77], off offset:256
	s_nop 1
	v_mov_b64_e32 v[76:77], v[210:211]
	v_mov_b64_e32 v[78:79], v[212:213]
	v_add_f32_e32 v90, v86, v87
	v_pk_fma_f32 v[78:79], v[154:155], v[62:63], v[78:79]
	v_pk_fma_f32 v[76:77], v[156:157], v[60:61], v[76:77]
	global_store_dwordx4 v[80:81], v[76:79], off offset:576
	v_pk_mul_f32 v[88:89], v[44:45], v[76:77]
	v_pk_mul_f32 v[86:87], v[46:47], v[78:79]
	v_mul_f32_e32 v77, v77, v77
	v_fmac_f32_e32 v77, v76, v76
	v_mul_f32_e32 v76, v79, v79
	v_fmac_f32_e32 v76, v78, v78
	v_and_b32_e32 v78, 64, v176
	v_add_f32_e32 v76, v77, v76
	v_xor_b32_e32 v77, 16, v176
	v_add_u32_e32 v78, 64, v78
	v_cmp_lt_i32_e32 vcc, v77, v78
	v_add_f32_e32 v76, v90, v76
	v_cvt_pk_bf16_f32 v88, v88, v89
	v_cvt_pk_bf16_f32 v89, v86, v87
	global_store_dwordx2 v[84:85], v[88:89], off offset:288
	v_cndmask_b32_e32 v77, v176, v77, vcc
	v_lshlrev_b32_e32 v77, 2, v77
	ds_bpermute_b32 v77, v77, v76
	s_waitcnt lgkmcnt(0)
	v_add_f32_e32 v76, v76, v77
	v_xor_b32_e32 v77, 32, v176
	v_cmp_lt_i32_e32 vcc, v77, v78
	s_nop 1
	v_cndmask_b32_e32 v77, v176, v77, vcc
	v_lshlrev_b32_e32 v77, 2, v77
	ds_bpermute_b32 v77, v77, v76
	s_and_saveexec_b64 s[0:1], s[38:39]
	s_cbranch_execz .LBB0_525
	v_lshl_add_u64 v[78:79], v[162:163], 2, s[20:21]
	s_waitcnt lgkmcnt(0)
	v_add_f32_e32 v76, v76, v77
	global_atomic_add_f32 v[78:79], v76, off offset:512

; __device__ __forceinline__ unsigned cvt_pk_bf16(float lo, float hi) { unsigned r; asm volatile("v_cvt_pk_bf16_f32 %0, %1, %2" : "=v"(r) : "v"(lo), "v"(hi)); return r; }
;     __device__ __forceinline__ void operator()(const f32x4 (&acc)[2][2][4][2], const Unit& u, int wr, int wc, int fr, int fq) const {
;         const int col0 = u.pn * BM + wc * 32 + 4 * fq;
;         f32x4 gv[2][2];
; #pragma unroll
;         for (int bj = 0; bj < 2; ++bj)
; #pragma unroll
;             for (int n = 0; n < 2; ++n) gv[bj][n] = gnext ? *(const f32x4*)(gnext + col0 + bj * HALF + n * 16) : (f32x4){0.f, 0.f, 0.f, 0.f};
; #pragma unroll
;         for (int ai = 0; ai < 2; ++ai)
; #pragma unroll
;             for (int m = 0; m < 4; ++m) { const int row = u.pm * BM + ai * HALF + wr * 64 + m * 16 + fr; const size_t off = (size_t)row * ldc + col0;
;                 float ssum = 0.f;
; #pragma unroll
;                 for (int bj = 0; bj < 2; ++bj)
; #pragma unroll
;                     for (int n = 0; n < 2; ++n) { f32x4* p = (f32x4*)(X + off + bj * HALF + n * 16); const f32x4 v = *(const f32x4*)(Xin + off + bj * HALF + n * 16) + acc[ai][bj][m][n] * scale; *p = v;
;                         if (gnext) { ssum += (v.x * v.x + v.y * v.y) + (v.z * v.z + v.w * v.w); const f32x4 o = v * gv[bj][n];
;                             u32x2 w; w.x = cvt_pk_bf16(o.x, o.y); w.y = cvt_pk_bf16(o.z, o.w); *(u32x2*)(XB + off + bj * HALF + n * 16) = w; } }
;                 if (gnext) { ssum += __shfl_xor(ssum, 16); ssum += __shfl_xor(ssum, 32); if (fq == 0) unsafeAtomicAdd(SS + row, ssum); } }
.LBB0_526:
	s_waitcnt lgkmcnt(0)
	s_nop 1
	v_mov_b64_e32 v[76:77], v[202:203]
	v_mov_b64_e32 v[78:79], v[204:205]
	v_mov_b32_e32 v155, v154
	v_pk_fma_f32 v[74:75], v[154:155], v[74:75], v[78:79]
	v_pk_fma_f32 v[72:73], v[156:157], v[72:73], v[76:77]
	global_store_dwordx4 v[80:81], v[72:75], off offset:64
	s_nop 1
	v_mov_b64_e32 v[72:73], v[206:207]
	v_mov_b64_e32 v[74:75], v[208:209]
	v_pk_fma_f32 v[70:71], v[154:155], v[70:71], v[74:75]
	v_pk_fma_f32 v[68:69], v[156:157], v[68:69], v[72:73]
	global_store_dwordx4 v[80:81], v[68:71], off offset:512
	s_nop 1
	v_mov_b64_e32 v[68:69], v[210:211]
	v_mov_b64_e32 v[70:71], v[212:213]
	v_pk_fma_f32 v[62:63], v[154:155], v[62:63], v[70:71]
	v_pk_fma_f32 v[60:61], v[156:157], v[60:61], v[68:69]
	global_store_dwordx4 v[80:81], v[60:63], off offset:576
.LBB0_527:
	s_nop 1
	v_add_u32_e32 v60, 0x90, v162
	v_ashrrev_i32_e32 v61, 31, v60
	v_lshlrev_b64 v[60:61], 11, v[60:61]
	v_lshl_add_u64 v[72:73], v[60:61], 0, v[164:165]
	v_lshlrev_b64 v[68:69], 2, v[72:73]
	v_lshl_add_u64 v[70:71], s[6:7], 0, v[68:69]
	s_nop 1
	v_mov_b64_e32 v[60:61], v[214:215]
	v_mov_b64_e32 v[62:63], v[216:217]
	v_mov_b32_e32 v155, v154
	v_lshl_add_u64 v[68:69], s[16:17], 0, v[68:69]
	s_and_b64 vcc, exec, s[42:43]
	v_pk_fma_f32 v[62:63], v[154:155], v[66:67], v[62:63]
	v_pk_fma_f32 v[60:61], v[156:157], v[64:65], v[60:61]
	global_store_dwordx4 v[68:69], v[60:63], off
	s_cbranch_vccnz .LBB0_550
	v_mul_f32_e32 v64, v61, v61
	v_mul_f32_e32 v65, v63, v63
	v_fmac_f32_e32 v64, v60, v60
	v_fmac_f32_e32 v65, v62, v62
	v_add_f32_e32 v66, v64, v65
	v_pk_mul_f32 v[60:61], v[56:57], v[60:61]
	v_lshl_add_u64 v[64:65], v[72:73], 1, s[10:11]
	v_pk_mul_f32 v[62:63], v[58:59], v[62:63]
	v_cvt_pk_bf16_f32 v60, v60, v61
	s_nop 0
	v_cvt_pk_bf16_f32 v61, v62, v63
	global_store_dwordx2 v[64:65], v[60:61], off
	s_nop 1
	v_mov_b64_e32 v[60:61], v[218:219]
	v_mov_b64_e32 v[62:63], v[220:221]
	v_pk_fma_f32 v[60:61], v[156:157], v[40:41], v[60:61]
	v_pk_fma_f32 v[62:63], v[154:155], v[42:43], v[62:63]
	v_mul_f32_e32 v67, v61, v61
	global_store_dwordx4 v[68:69], v[60:63], off offset:64
	v_fmac_f32_e32 v67, v60, v60
	v_mul_f32_e32 v72, v63, v63
	v_pk_mul_f32 v[60:61], v[48:49], v[60:61]
	v_fmac_f32_e32 v72, v62, v62
	v_pk_mul_f32 v[62:63], v[50:51], v[62:63]
	v_cvt_pk_bf16_f32 v60, v60, v61
	v_add_f32_e32 v67, v67, v72
	v_cvt_pk_bf16_f32 v61, v62, v63
	global_store_dwordx2 v[64:65], v[60:61], off offset:32
	s_nop 1
	v_mov_b64_e32 v[60:61], v[222:223]
	v_mov_b64_e32 v[62:63], v[224:225]
	v_add_f32_e32 v66, v66, v67
	v_pk_fma_f32 v[60:61], v[156:157], v[36:37], v[60:61]
	v_pk_fma_f32 v[62:63], v[154:155], v[38:39], v[62:63]
	v_mul_f32_e32 v67, v61, v61
	global_store_dwordx4 v[68:69], v[60:63], off offset:512
	v_fmac_f32_e32 v67, v60, v60
	v_mul_f32_e32 v72, v63, v63
	v_pk_mul_f32 v[60:61], v[52:53], v[60:61]
	v_fmac_f32_e32 v72, v62, v62
	v_pk_mul_f32 v[62:63], v[54:55], v[62:63]
	v_cvt_pk_bf16_f32 v60, v60, v61
	v_add_f32_e32 v67, v67, v72
	v_cvt_pk_bf16_f32 v61, v62, v63
	global_store_dwordx2 v[64:65], v[60:61], off offset:256
	s_nop 1
	v_mov_b64_e32 v[60:61], v[226:227]
	v_mov_b64_e32 v[62:63], v[228:229]
	v_add_f32_e32 v74, v66, v67
	v_pk_fma_f32 v[62:63], v[154:155], v[30:31], v[62:63]
	v_pk_fma_f32 v[60:61], v[156:157], v[28:29], v[60:61]
	global_store_dwordx4 v[68:69], v[60:63], off offset:576
	v_pk_mul_f32 v[72:73], v[44:45], v[60:61]
	v_pk_mul_f32 v[66:67], v[46:47], v[62:63]
	v_mul_f32_e32 v61, v61, v61
	v_fmac_f32_e32 v61, v60, v60
	v_mul_f32_e32 v60, v63, v63
	v_fmac_f32_e32 v60, v62, v62
	v_and_b32_e32 v62, 64, v176
	v_add_f32_e32 v60, v61, v60
	v_xor_b32_e32 v61, 16, v176
	v_add_u32_e32 v62, 64, v62
	v_cmp_lt_i32_e32 vcc, v61, v62
	v_add_f32_e32 v60, v74, v60
	v_cvt_pk_bf16_f32 v72, v72, v73
	v_cvt_pk_bf16_f32 v73, v66, v67
	global_store_dwordx2 v[64:65], v[72:73], off offset:288
	v_cndmask_b32_e32 v61, v176, v61, vcc
	v_lshlrev_b32_e32 v61, 2, v61
	ds_bpermute_b32 v61, v61, v60
	s_waitcnt lgkmcnt(0)
	v_add_f32_e32 v60, v60, v61
	v_xor_b32_e32 v61, 32, v176
	v_cmp_lt_i32_e32 vcc, v61, v62
	s_nop 1
	v_cndmask_b32_e32 v61, v176, v61, vcc
	v_lshlrev_b32_e32 v61, 2, v61
	ds_bpermute_b32 v61, v61, v60
	s_and_saveexec_b64 s[0:1], s[38:39]
	s_cbranch_execz .LBB0_530
	v_lshl_add_u64 v[62:63], v[162:163], 2, s[20:21]
	s_waitcnt lgkmcnt(0)
	v_add_f32_e32 v60, v60, v61
	global_atomic_add_f32 v[62:63], v60, off offset:576

; __device__ __forceinline__ unsigned cvt_pk_bf16(float lo, float hi) { unsigned r; asm volatile("v_cvt_pk_bf16_f32 %0, %1, %2" : "=v"(r) : "v"(lo), "v"(hi)); return r; }
;     __device__ __forceinline__ void operator()(const f32x4 (&acc)[2][2][4][2], const Unit& u, int wr, int wc, int fr, int fq) const {
;         const int col0 = u.pn * BM + wc * 32 + 4 * fq;
;         f32x4 gv[2][2];
; #pragma unroll
;         for (int bj = 0; bj < 2; ++bj)
; #pragma unroll
;             for (int n = 0; n < 2; ++n) gv[bj][n] = gnext ? *(const f32x4*)(gnext + col0 + bj * HALF + n * 16) : (f32x4){0.f, 0.f, 0.f, 0.f};
; #pragma unroll
;         for (int ai = 0; ai < 2; ++ai)
; #pragma unroll
;             for (int m = 0; m < 4; ++m) { const int row = u.pm * BM + ai * HALF + wr * 64 + m * 16 + fr; const size_t off = (size_t)row * ldc + col0;
;                 float ssum = 0.f;
; #pragma unroll
;                 for (int bj = 0; bj < 2; ++bj)
; #pragma unroll
;                     for (int n = 0; n < 2; ++n) { f32x4* p = (f32x4*)(X + off + bj * HALF + n * 16); const f32x4 v = *(const f32x4*)(Xin + off + bj * HALF + n * 16) + acc[ai][bj][m][n] * scale; *p = v;
;                         if (gnext) { ssum += (v.x * v.x + v.y * v.y) + (v.z * v.z + v.w * v.w); const f32x4 o = v * gv[bj][n];
;                             u32x2 w; w.x = cvt_pk_bf16(o.x, o.y); w.y = cvt_pk_bf16(o.z, o.w); *(u32x2*)(XB + off + bj * HALF + n * 16) = w; } }
;                 if (gnext) { ssum += __shfl_xor(ssum, 16); ssum += __shfl_xor(ssum, 32); if (fq == 0) unsafeAtomicAdd(SS + row, ssum); } }
.LBB0_531:
	s_waitcnt lgkmcnt(0)
	s_nop 1
	v_mov_b64_e32 v[60:61], v[218:219]
	v_mov_b64_e32 v[62:63], v[220:221]
	v_mov_b32_e32 v155, v154
	v_pk_fma_f32 v[42:43], v[154:155], v[42:43], v[62:63]
	v_pk_fma_f32 v[40:41], v[156:157], v[40:41], v[60:61]
	global_store_dwordx4 v[68:69], v[40:43], off offset:64
	s_nop 1
	v_mov_b64_e32 v[40:41], v[222:223]
	v_mov_b64_e32 v[42:43], v[224:225]
	v_pk_fma_f32 v[38:39], v[154:155], v[38:39], v[42:43]
	v_pk_fma_f32 v[36:37], v[156:157], v[36:37], v[40:41]
	global_store_dwordx4 v[68:69], v[36:39], off offset:512
	s_nop 1
	v_mov_b64_e32 v[36:37], v[226:227]
	v_mov_b64_e32 v[38:39], v[228:229]
	v_pk_fma_f32 v[30:31], v[154:155], v[30:31], v[38:39]
	v_pk_fma_f32 v[28:29], v[156:157], v[28:29], v[36:37]
	global_store_dwordx4 v[68:69], v[28:31], off offset:576
.LBB0_532:
	s_nop 1
	v_add_u32_e32 v194, 0xa0, v162
	v_ashrrev_i32_e32 v195, 31, v194
	v_lshlrev_b64 v[194:195], 11, v[194:195]
	v_lshl_add_u64 v[194:195], v[194:195], 0, v[164:165]
	v_lshlrev_b64 v[194:195], 2, v[194:195]
	v_lshl_add_u64 v[194:195], s[6:7], 0, v[194:195]
	global_load_dwordx4 v[198:201], v[194:195], off
	global_load_dwordx4 v[202:205], v[194:195], off offset:64
	global_load_dwordx4 v[206:209], v[194:195], off offset:512
	global_load_dwordx4 v[210:213], v[194:195], off offset:576
	v_add_u32_e32 v196, 0xb0, v162
	v_ashrrev_i32_e32 v197, 31, v196
	v_lshlrev_b64 v[196:197], 11, v[196:197]
	v_lshl_add_u64 v[196:197], v[196:197], 0, v[164:165]
	v_lshlrev_b64 v[196:197], 2, v[196:197]
	v_lshl_add_u64 v[196:197], s[6:7], 0, v[196:197]
	global_load_dwordx4 v[214:217], v[196:197], off
	global_load_dwordx4 v[218:221], v[196:197], off offset:64
	global_load_dwordx4 v[222:225], v[196:197], off offset:512
	global_load_dwordx4 v[226:229], v[196:197], off offset:576
	s_waitcnt vmcnt(0)
	v_add_u32_e32 v28, 0xa0, v162
	v_ashrrev_i32_e32 v29, 31, v28
	v_lshlrev_b64 v[28:29], 11, v[28:29]
	v_lshl_add_u64 v[40:41], v[28:29], 0, v[164:165]
	v_lshlrev_b64 v[36:37], 2, v[40:41]
	v_lshl_add_u64 v[38:39], s[6:7], 0, v[36:37]
	s_nop 1
	v_mov_b64_e32 v[28:29], v[198:199]
	v_mov_b64_e32 v[30:31], v[200:201]
	v_mov_b32_e32 v155, v154
	v_lshl_add_u64 v[36:37], s[16:17], 0, v[36:37]
	s_and_b64 vcc, exec, s[42:43]
	v_pk_fma_f32 v[30:31], v[154:155], v[34:35], v[30:31]
	v_pk_fma_f32 v[28:29], v[156:157], v[32:33], v[28:29]
	global_store_dwordx4 v[36:37], v[28:31], off
	s_cbranch_vccnz .LBB0_551
	v_mul_f32_e32 v32, v29, v29
	v_mul_f32_e32 v33, v31, v31
	v_fmac_f32_e32 v32, v28, v28
	v_fmac_f32_e32 v33, v30, v30
	v_add_f32_e32 v34, v32, v33
	v_pk_mul_f32 v[28:29], v[56:57], v[28:29]
	v_lshl_add_u64 v[32:33], v[40:41], 1, s[10:11]
	v_pk_mul_f32 v[30:31], v[58:59], v[30:31]
	v_cvt_pk_bf16_f32 v28, v28, v29
	s_nop 0
	v_cvt_pk_bf16_f32 v29, v30, v31
	global_store_dwordx2 v[32:33], v[28:29], off
	s_nop 1
	v_mov_b64_e32 v[28:29], v[202:203]
	v_mov_b64_e32 v[30:31], v[204:205]
	v_pk_fma_f32 v[28:29], v[156:157], v[24:25], v[28:29]
	v_pk_fma_f32 v[30:31], v[154:155], v[26:27], v[30:31]
	v_mul_f32_e32 v35, v29, v29
	global_store_dwordx4 v[36:37], v[28:31], off offset:64
	v_fmac_f32_e32 v35, v28, v28
	v_mul_f32_e32 v40, v31, v31
	v_pk_mul_f32 v[28:29], v[48:49], v[28:29]
	v_fmac_f32_e32 v40, v30, v30
	v_pk_mul_f32 v[30:31], v[50:51], v[30:31]
	v_cvt_pk_bf16_f32 v28, v28, v29
	v_add_f32_e32 v35, v35, v40
	v_cvt_pk_bf16_f32 v29, v30, v31
	global_store_dwordx2 v[32:33], v[28:29], off offset:32
	s_nop 1
	v_mov_b64_e32 v[28:29], v[206:207]
	v_mov_b64_e32 v[30:31], v[208:209]
	v_add_f32_e32 v34, v34, v35
	v_pk_fma_f32 v[28:29], v[156:157], v[20:21], v[28:29]
	v_pk_fma_f32 v[30:31], v[154:155], v[22:23], v[30:31]
	v_mul_f32_e32 v35, v29, v29
	global_store_dwordx4 v[36:37], v[28:31], off offset:512
	v_fmac_f32_e32 v35, v28, v28
	v_mul_f32_e32 v40, v31, v31
	v_pk_mul_f32 v[28:29], v[52:53], v[28:29]
	v_fmac_f32_e32 v40, v30, v30
	v_pk_mul_f32 v[30:31], v[54:55], v[30:31]
	v_cvt_pk_bf16_f32 v28, v28, v29
	v_add_f32_e32 v35, v35, v40
	v_cvt_pk_bf16_f32 v29, v30, v31
	global_store_dwordx2 v[32:33], v[28:29], off offset:256
	s_nop 1
	v_mov_b64_e32 v[28:29], v[210:211]
	v_mov_b64_e32 v[30:31], v[212:213]
	v_add_f32_e32 v42, v34, v35
	v_pk_fma_f32 v[30:31], v[154:155], v[14:15], v[30:31]
	v_pk_fma_f32 v[28:29], v[156:157], v[12:13], v[28:29]
	global_store_dwordx4 v[36:37], v[28:31], off offset:576
	v_pk_mul_f32 v[40:41], v[44:45], v[28:29]
	v_pk_mul_f32 v[34:35], v[46:47], v[30:31]
	v_mul_f32_e32 v29, v29, v29
	v_fmac_f32_e32 v29, v28, v28
	v_mul_f32_e32 v28, v31, v31
	v_fmac_f32_e32 v28, v30, v30
	v_and_b32_e32 v30, 64, v176
	v_add_f32_e32 v28, v29, v28
	v_xor_b32_e32 v29, 16, v176
	v_add_u32_e32 v30, 64, v30
	v_cmp_lt_i32_e32 vcc, v29, v30
	v_add_f32_e32 v28, v42, v28
	v_cvt_pk_bf16_f32 v40, v40, v41
	v_cvt_pk_bf16_f32 v41, v34, v35
	global_store_dwordx2 v[32:33], v[40:41], off offset:288
	v_cndmask_b32_e32 v29, v176, v29, vcc
	v_lshlrev_b32_e32 v29, 2, v29
	ds_bpermute_b32 v29, v29, v28
	s_waitcnt lgkmcnt(0)
	v_add_f32_e32 v28, v28, v29
	v_xor_b32_e32 v29, 32, v176
	v_cmp_lt_i32_e32 vcc, v29, v30
	s_nop 1
	v_cndmask_b32_e32 v29, v176, v29, vcc
	v_lshlrev_b32_e32 v29, 2, v29
	ds_bpermute_b32 v29, v29, v28
	s_and_saveexec_b64 s[0:1], s[38:39]
	s_cbranch_execz .LBB0_535
	v_lshl_add_u64 v[30:31], v[162:163], 2, s[20:21]
	s_waitcnt lgkmcnt(0)
	v_add_f32_e32 v28, v28, v29
	global_atomic_add_f32 v[30:31], v28, off offset:640

; __device__ __forceinline__ unsigned cvt_pk_bf16(float lo, float hi) { unsigned r; asm volatile("v_cvt_pk_bf16_f32 %0, %1, %2" : "=v"(r) : "v"(lo), "v"(hi)); return r; }
;     __device__ __forceinline__ void operator()(const f32x4 (&acc)[2][2][4][2], const Unit& u, int wr, int wc, int fr, int fq) const {
;         const int col0 = u.pn * BM + wc * 32 + 4 * fq;
;         f32x4 gv[2][2];
; #pragma unroll
;         for (int bj = 0; bj < 2; ++bj)
; #pragma unroll
;             for (int n = 0; n < 2; ++n) gv[bj][n] = gnext ? *(const f32x4*)(gnext + col0 + bj * HALF + n * 16) : (f32x4){0.f, 0.f, 0.f, 0.f};
; #pragma unroll
;         for (int ai = 0; ai < 2; ++ai)
; #pragma unroll
;             for (int m = 0; m < 4; ++m) { const int row = u.pm * BM + ai * HALF + wr * 64 + m * 16 + fr; const size_t off = (size_t)row * ldc + col0;
;                 float ssum = 0.f;
; #pragma unroll
;                 for (int bj = 0; bj < 2; ++bj)
; #pragma unroll
;                     for (int n = 0; n < 2; ++n) { f32x4* p = (f32x4*)(X + off + bj * HALF + n * 16); const f32x4 v = *(const f32x4*)(Xin + off + bj * HALF + n * 16) + acc[ai][bj][m][n] * scale; *p = v;
;                         if (gnext) { ssum += (v.x * v.x + v.y * v.y) + (v.z * v.z + v.w * v.w); const f32x4 o = v * gv[bj][n];
;                             u32x2 w; w.x = cvt_pk_bf16(o.x, o.y); w.y = cvt_pk_bf16(o.z, o.w); *(u32x2*)(XB + off + bj * HALF + n * 16) = w; } }
;                 if (gnext) { ssum += __shfl_xor(ssum, 16); ssum += __shfl_xor(ssum, 32); if (fq == 0) unsafeAtomicAdd(SS + row, ssum); } }
.LBB0_536:
	s_waitcnt lgkmcnt(0)
	s_nop 1
	v_mov_b64_e32 v[28:29], v[202:203]
	v_mov_b64_e32 v[30:31], v[204:205]
	v_mov_b32_e32 v155, v154
	v_pk_fma_f32 v[26:27], v[154:155], v[26:27], v[30:31]
	v_pk_fma_f32 v[24:25], v[156:157], v[24:25], v[28:29]
	global_store_dwordx4 v[36:37], v[24:27], off offset:64
	s_nop 1
	v_mov_b64_e32 v[24:25], v[206:207]
	v_mov_b64_e32 v[26:27], v[208:209]
	v_pk_fma_f32 v[22:23], v[154:155], v[22:23], v[26:27]
	v_pk_fma_f32 v[20:21], v[156:157], v[20:21], v[24:25]
	global_store_dwordx4 v[36:37], v[20:23], off offset:512
	s_nop 1
	v_mov_b64_e32 v[20:21], v[210:211]
	v_mov_b64_e32 v[22:23], v[212:213]
	v_pk_fma_f32 v[14:15], v[154:155], v[14:15], v[22:23]
	v_pk_fma_f32 v[12:13], v[156:157], v[12:13], v[20:21]
	global_store_dwordx4 v[36:37], v[12:15], off offset:576
.LBB0_537:
	s_nop 1
	v_add_u32_e32 v12, 0xb0, v162
	v_ashrrev_i32_e32 v13, 31, v12
	v_lshlrev_b64 v[12:13], 11, v[12:13]
	v_lshl_add_u64 v[24:25], v[12:13], 0, v[164:165]
	v_lshlrev_b64 v[20:21], 2, v[24:25]
	v_lshl_add_u64 v[22:23], s[6:7], 0, v[20:21]
	s_nop 1
	v_mov_b64_e32 v[12:13], v[214:215]
	v_mov_b64_e32 v[14:15], v[216:217]
	v_mov_b32_e32 v155, v154
	v_lshl_add_u64 v[20:21], s[16:17], 0, v[20:21]
	s_and_b64 vcc, exec, s[42:43]
	v_pk_fma_f32 v[14:15], v[154:155], v[18:19], v[14:15]
	v_pk_fma_f32 v[12:13], v[156:157], v[16:17], v[12:13]
	global_store_dwordx4 v[20:21], v[12:15], off
	s_cbranch_vccnz .LBB0_552
	v_pk_mul_f32 v[18:19], v[56:57], v[12:13]
	v_lshl_add_u64 v[32:33], v[24:25], 1, s[10:11]
	v_pk_mul_f32 v[16:17], v[58:59], v[14:15]
	v_cvt_pk_bf16_f32 v18, v18, v19
	v_mul_f32_e32 v13, v13, v13
	v_cvt_pk_bf16_f32 v19, v16, v17
	global_store_dwordx2 v[32:33], v[18:19], off
	s_nop 1
	v_mov_b64_e32 v[16:17], v[218:219]
	v_mov_b64_e32 v[18:19], v[220:221]
	v_and_b32_e32 v35, 64, v176
	v_xor_b32_e32 v34, 16, v176
	v_fmac_f32_e32 v13, v12, v12
	v_add_u32_e32 v12, 64, v35
	v_mul_f32_e32 v15, v15, v15
	v_cmp_lt_i32_e32 vcc, v34, v12
	v_fmac_f32_e32 v15, v14, v14
	v_add_f32_e32 v13, v13, v15
	v_cndmask_b32_e32 v14, v176, v34, vcc
	v_lshlrev_b32_e32 v34, 2, v14
	v_xor_b32_e32 v36, 32, v176
	v_cmp_lt_i32_e32 vcc, v36, v12
	v_pk_fma_f32 v[16:17], v[156:157], v[8:9], v[16:17]
	v_pk_fma_f32 v[18:19], v[154:155], v[10:11], v[18:19]
	v_pk_mul_f32 v[26:27], v[48:49], v[16:17]
	global_store_dwordx4 v[20:21], v[16:19], off offset:64
	v_pk_mul_f32 v[24:25], v[50:51], v[18:19]
	v_cvt_pk_bf16_f32 v26, v26, v27
	v_mul_f32_e32 v14, v17, v17
	v_cvt_pk_bf16_f32 v27, v24, v25
	global_store_dwordx2 v[32:33], v[26:27], off offset:32
	s_nop 1
	v_mov_b64_e32 v[24:25], v[222:223]
	v_mov_b64_e32 v[26:27], v[224:225]
	v_mul_f32_e32 v15, v19, v19
	v_fmac_f32_e32 v14, v16, v16
	v_fmac_f32_e32 v15, v18, v18
	v_add_f32_e32 v14, v14, v15
	v_add_f32_e32 v13, v13, v14
	v_pk_fma_f32 v[24:25], v[156:157], v[4:5], v[24:25]
	v_pk_fma_f32 v[26:27], v[154:155], v[6:7], v[26:27]
	v_pk_mul_f32 v[30:31], v[52:53], v[24:25]
	global_store_dwordx4 v[20:21], v[24:27], off offset:512
	s_waitcnt lgkmcnt(0)
	v_pk_mul_f32 v[28:29], v[54:55], v[26:27]
	v_cvt_pk_bf16_f32 v30, v30, v31
	v_mul_f32_e32 v14, v25, v25
	v_cvt_pk_bf16_f32 v31, v28, v29
	global_store_dwordx2 v[32:33], v[30:31], off offset:256
	s_nop 1
	v_mov_b64_e32 v[28:29], v[226:227]
	v_mov_b64_e32 v[30:31], v[228:229]
	v_mul_f32_e32 v15, v27, v27
	v_fmac_f32_e32 v14, v24, v24
	v_fmac_f32_e32 v15, v26, v26
	v_add_f32_e32 v14, v14, v15
	v_add_f32_e32 v13, v13, v14
	v_pk_fma_f32 v[16:17], v[154:155], v[2:3], v[30:31]
	v_pk_fma_f32 v[14:15], v[156:157], v[0:1], v[28:29]
	v_mul_f32_e32 v19, v17, v17
	v_mul_f32_e32 v18, v15, v15
	v_fmac_f32_e32 v18, v14, v14
	v_fmac_f32_e32 v19, v16, v16
	v_add_f32_e32 v18, v18, v19
	v_add_f32_e32 v13, v13, v18
	ds_bpermute_b32 v18, v34, v13
	v_cndmask_b32_e32 v19, v176, v36, vcc
	global_store_dwordx4 v[20:21], v[14:17], off offset:576
	s_waitcnt lgkmcnt(0)
	v_add_f32_e32 v12, v13, v18
	v_lshlrev_b32_e32 v13, 2, v19
	ds_bpermute_b32 v13, v13, v12
	v_pk_mul_f32 v[14:15], v[44:45], v[14:15]
	v_pk_mul_f32 v[16:17], v[46:47], v[16:17]
	v_cvt_pk_bf16_f32 v14, v14, v15
	s_nop 0
	v_cvt_pk_bf16_f32 v15, v16, v17
	global_store_dwordx2 v[32:33], v[14:15], off offset:288
	s_and_saveexec_b64 s[0:1], s[38:39]
	s_cbranch_execz .LBB0_540
	v_lshl_add_u64 v[14:15], v[162:163], 2, s[20:21]
	s_waitcnt lgkmcnt(0)
	v_add_f32_e32 v12, v12, v13
	global_atomic_add_f32 v[14:15], v12, off offset:704

; __device__ __forceinline__ unsigned cvt_pk_bf16(float lo, float hi) { unsigned r; asm volatile("v_cvt_pk_bf16_f32 %0, %1, %2" : "=v"(r) : "v"(lo), "v"(hi)); return r; }
;     __device__ __forceinline__ void operator()(const f32x4 (&acc)[2][2][4][2], const Unit& u, int wr, int wc, int fr, int fq) const {
;         const int col0 = u.pn * BM + wc * 32 + 4 * fq;
;         f32x4 gv[2][2];
; #pragma unroll
;         for (int bj = 0; bj < 2; ++bj)
; #pragma unroll
;             for (int n = 0; n < 2; ++n) gv[bj][n] = gnext ? *(const f32x4*)(gnext + col0 + bj * HALF + n * 16) : (f32x4){0.f, 0.f, 0.f, 0.f};
; #pragma unroll
;         for (int ai = 0; ai < 2; ++ai)
; #pragma unroll
;             for (int m = 0; m < 4; ++m) { const int row = u.pm * BM + ai * HALF + wr * 64 + m * 16 + fr; const size_t off = (size_t)row * ldc + col0;
;                 float ssum = 0.f;
; #pragma unroll
;                 for (int bj = 0; bj < 2; ++bj)
; #pragma unroll
;                     for (int n = 0; n < 2; ++n) { f32x4* p = (f32x4*)(X + off + bj * HALF + n * 16); const f32x4 v = *(const f32x4*)(Xin + off + bj * HALF + n * 16) + acc[ai][bj][m][n] * scale; *p = v;
;                         if (gnext) { ssum += (v.x * v.x + v.y * v.y) + (v.z * v.z + v.w * v.w); const f32x4 o = v * gv[bj][n];
;                             u32x2 w; w.x = cvt_pk_bf16(o.x, o.y); w.y = cvt_pk_bf16(o.z, o.w); *(u32x2*)(XB + off + bj * HALF + n * 16) = w; } }
;                 if (gnext) { ssum += __shfl_xor(ssum, 16); ssum += __shfl_xor(ssum, 32); if (fq == 0) unsafeAtomicAdd(SS + row, ssum); } }
.LBB0_541:
	s_waitcnt lgkmcnt(0)
	s_nop 1
	v_mov_b64_e32 v[12:13], v[218:219]
	v_mov_b64_e32 v[14:15], v[220:221]
	v_mov_b32_e32 v155, v154
	v_pk_fma_f32 v[10:11], v[154:155], v[10:11], v[14:15]
	v_pk_fma_f32 v[8:9], v[156:157], v[8:9], v[12:13]
	global_store_dwordx4 v[20:21], v[8:11], off offset:64
	s_nop 1
	v_mov_b64_e32 v[8:9], v[222:223]
	v_mov_b64_e32 v[10:11], v[224:225]
	v_pk_fma_f32 v[6:7], v[154:155], v[6:7], v[10:11]
	v_pk_fma_f32 v[4:5], v[156:157], v[4:5], v[8:9]
	global_store_dwordx4 v[20:21], v[4:7], off offset:512
	s_nop 1
	v_mov_b64_e32 v[4:5], v[226:227]
	v_mov_b64_e32 v[6:7], v[228:229]
	v_pk_fma_f32 v[2:3], v[154:155], v[2:3], v[6:7]
	v_pk_fma_f32 v[0:1], v[156:157], v[0:1], v[4:5]
	global_store_dwordx4 v[20:21], v[0:3], off offset:576
